# load segments issue the two LDS-DMA pieces before the ds_reads
# speedup vs baseline: 1.0071x; 1.0071x over previous
.Lg131_noy:
	s_add_u32 s26, s20, 0xfffc0080
	s_addc_u32 s27, s21, -1
	s_cmp_eq_u32 s57, 12
	s_cselect_b32 s29, s13, s27
	s_cselect_b32 s28, s53, s26
	s_cselect_b32 s27, s11, s56
	s_cselect_b32 s26, s54, s55
	s_add_i32 m0, s19, 0xc000
	s_nop 0
	global_load_lds_dwordx4 v136, s[20:21]
	s_add_i32 m0, s19, 0xe000
	s_nop 0
	global_load_lds_dwordx4 v138, s[20:21]
	ds_read_b128 v[152:155], v149
	ds_read_b128 v[156:159], v149 offset:1024
	ds_read_b128 v[160:163], v149 offset:2048
	ds_read_b128 v[164:167], v149 offset:3072
	ds_read_b128 v[168:171], v150
	ds_read_b128 v[172:175], v150 offset:1024
	ds_read_b128 v[176:179], v150 offset:2048
	ds_read_b128 v[180:183], v150 offset:3072
	ds_read_b128 v[184:187], v150 offset:4096
	ds_read_b128 v[188:191], v150 offset:5120
	ds_read_b128 v[192:195], v150 offset:6144
	ds_read_b128 v[196:199], v150 offset:7168
	s_waitcnt lgkmcnt(8)
	s_barrier
	s_waitcnt lgkmcnt(0)
	s_waitcnt lgkmcnt(0)
	v_mfma_f32_16x16x32_bf16 v[124:127], v[152:155], v[168:171], 0
	v_mfma_f32_16x16x32_bf16 v[120:123], v[160:163], v[168:171], 0
	v_mfma_f32_16x16x32_bf16 v[108:111], v[152:155], v[176:179], 0
	v_mfma_f32_16x16x32_bf16 v[104:107], v[160:163], v[176:179], 0
	v_mfma_f32_16x16x32_bf16 v[92:95], v[152:155], v[184:187], 0
	v_mfma_f32_16x16x32_bf16 v[88:91], v[160:163], v[184:187], 0
	v_mfma_f32_16x16x32_bf16 v[76:79], v[152:155], v[192:195], 0
	v_mfma_f32_16x16x32_bf16 v[72:75], v[160:163], v[192:195], 0
	v_mfma_f32_16x16x32_bf16 v[124:127], v[156:159], v[172:175], v[124:127]
	v_mfma_f32_16x16x32_bf16 v[120:123], v[164:167], v[172:175], v[120:123]
	v_mfma_f32_16x16x32_bf16 v[108:111], v[156:159], v[180:183], v[108:111]
	v_mfma_f32_16x16x32_bf16 v[104:107], v[164:167], v[180:183], v[104:107]
	v_mfma_f32_16x16x32_bf16 v[92:95], v[156:159], v[188:191], v[92:95]
	v_mfma_f32_16x16x32_bf16 v[88:91], v[164:167], v[188:191], v[88:91]
	v_mfma_f32_16x16x32_bf16 v[76:79], v[156:159], v[196:199], v[76:79]
	v_mfma_f32_16x16x32_bf16 v[72:75], v[164:167], v[196:199], v[72:75]
	s_barrier
	s_add_i32 s58, s47, s38
	s_add_u32 s80, s26, 0x80
	s_addc_u32 s81, s27, 0
	s_mov_b32 m0, s58
	s_nop 0
	global_load_lds_dwordx4 v132, s[26:27]
	s_add_i32 m0, s58, 0x2000
	s_nop 0
	global_load_lds_dwordx4 v128, s[26:27]
	ds_read_b128 v[200:203], v151
	ds_read_b128 v[204:207], v151 offset:1024
	ds_read_b128 v[208:211], v151 offset:2048
	ds_read_b128 v[212:215], v151 offset:3072
	s_waitcnt vmcnt(10)
	s_barrier
	s_waitcnt lgkmcnt(0)
	s_waitcnt lgkmcnt(0)
	v_mfma_f32_16x16x32_bf16 v[116:119], v[200:203], v[168:171], 0
	v_mfma_f32_16x16x32_bf16 v[112:115], v[208:211], v[168:171], 0
	v_mfma_f32_16x16x32_bf16 v[100:103], v[200:203], v[176:179], 0
	v_mfma_f32_16x16x32_bf16 v[96:99], v[208:211], v[176:179], 0
	v_mfma_f32_16x16x32_bf16 v[84:87], v[200:203], v[184:187], 0
	v_mfma_f32_16x16x32_bf16 v[80:83], v[208:211], v[184:187], 0
	v_mfma_f32_16x16x32_bf16 v[68:71], v[200:203], v[192:195], 0
	v_mfma_f32_16x16x32_bf16 v[64:67], v[208:211], v[192:195], 0
	v_mfma_f32_16x16x32_bf16 v[116:119], v[204:207], v[172:175], v[116:119]
	v_mfma_f32_16x16x32_bf16 v[112:115], v[212:215], v[172:175], v[112:115]
	v_mfma_f32_16x16x32_bf16 v[100:103], v[204:207], v[180:183], v[100:103]
	v_mfma_f32_16x16x32_bf16 v[96:99], v[212:215], v[180:183], v[96:99]
	v_mfma_f32_16x16x32_bf16 v[84:87], v[204:207], v[188:191], v[84:87]
	v_mfma_f32_16x16x32_bf16 v[80:83], v[212:215], v[188:191], v[80:83]
	v_mfma_f32_16x16x32_bf16 v[68:71], v[204:207], v[196:199], v[68:71]
	v_mfma_f32_16x16x32_bf16 v[64:67], v[212:215], v[196:199], v[64:67]
	s_mov_b32 m0, s19
	s_add_u32 s82, s28, 0x80
	s_addc_u32 s83, s29, 0
	s_barrier
	global_load_lds_dwordx4 v134, s[28:29]
	s_mov_b32 m0, s42
	s_nop 0
	global_load_lds_dwordx4 v130, s[28:29]
	ds_read_b128 v[168:171], v150 offset:16384
	ds_read_b128 v[172:175], v150 offset:17408
	ds_read_b128 v[176:179], v150 offset:18432
	ds_read_b128 v[180:183], v150 offset:19456
	ds_read_b128 v[184:187], v150 offset:20480
	ds_read_b128 v[188:191], v150 offset:21504
	ds_read_b128 v[192:195], v150 offset:22528
	ds_read_b128 v[196:199], v150 offset:23552
	s_barrier
	s_waitcnt lgkmcnt(0)
	s_waitcnt lgkmcnt(0)
	v_mfma_f32_16x16x32_bf16 v[60:63], v[152:155], v[168:171], 0
	v_mfma_f32_16x16x32_bf16 v[56:59], v[160:163], v[168:171], 0
	v_mfma_f32_16x16x32_bf16 v[44:47], v[152:155], v[176:179], 0
	v_mfma_f32_16x16x32_bf16 v[40:43], v[160:163], v[176:179], 0
	v_mfma_f32_16x16x32_bf16 v[28:31], v[152:155], v[184:187], 0
	v_mfma_f32_16x16x32_bf16 v[24:27], v[160:163], v[184:187], 0
	v_mfma_f32_16x16x32_bf16 v[12:15], v[152:155], v[192:195], 0
	v_mfma_f32_16x16x32_bf16 v[8:11], v[160:163], v[192:195], 0
	v_mfma_f32_16x16x32_bf16 v[60:63], v[156:159], v[172:175], v[60:63]
	v_mfma_f32_16x16x32_bf16 v[56:59], v[164:167], v[172:175], v[56:59]
	v_mfma_f32_16x16x32_bf16 v[44:47], v[156:159], v[180:183], v[44:47]
	v_mfma_f32_16x16x32_bf16 v[40:43], v[164:167], v[180:183], v[40:43]
	v_mfma_f32_16x16x32_bf16 v[28:31], v[156:159], v[188:191], v[28:31]
	v_mfma_f32_16x16x32_bf16 v[24:27], v[164:167], v[188:191], v[24:27]
	v_mfma_f32_16x16x32_bf16 v[12:15], v[156:159], v[196:199], v[12:15]
	v_mfma_f32_16x16x32_bf16 v[8:11], v[164:167], v[196:199], v[8:11]
	s_barrier
	s_add_u32 s58, s26, 0x40000
	s_addc_u32 s59, s27, 0
	s_add_i32 s60, s48, s38
	s_mov_b32 m0, s60
	s_nop 0
	global_load_lds_dwordx4 v132, s[58:59]
	s_add_i32 m0, s60, 0x2000
	s_nop 0
	global_load_lds_dwordx4 v128, s[58:59]
	s_waitcnt vmcnt(8)
	s_barrier
	v_mfma_f32_16x16x32_bf16 v[52:55], v[200:203], v[168:171], 0
	v_mfma_f32_16x16x32_bf16 v[48:51], v[208:211], v[168:171], 0
	v_mfma_f32_16x16x32_bf16 v[36:39], v[200:203], v[176:179], 0
	v_mfma_f32_16x16x32_bf16 v[32:35], v[208:211], v[176:179], 0
	v_mfma_f32_16x16x32_bf16 v[20:23], v[200:203], v[184:187], 0
	v_mfma_f32_16x16x32_bf16 v[16:19], v[208:211], v[184:187], 0
	v_mfma_f32_16x16x32_bf16 v[4:7], v[200:203], v[192:195], 0
	v_mfma_f32_16x16x32_bf16 v[0:3], v[208:211], v[192:195], 0
	v_mfma_f32_16x16x32_bf16 v[52:55], v[204:207], v[172:175], v[52:55]
	v_mfma_f32_16x16x32_bf16 v[48:51], v[212:215], v[172:175], v[48:51]
	v_mfma_f32_16x16x32_bf16 v[36:39], v[204:207], v[180:183], v[36:39]
	v_mfma_f32_16x16x32_bf16 v[32:35], v[212:215], v[180:183], v[32:35]
	v_mfma_f32_16x16x32_bf16 v[20:23], v[204:207], v[188:191], v[20:23]
	v_mfma_f32_16x16x32_bf16 v[16:19], v[212:215], v[188:191], v[16:19]
	v_mfma_f32_16x16x32_bf16 v[4:7], v[204:207], v[196:199], v[4:7]
	v_mfma_f32_16x16x32_bf16 v[0:3], v[212:215], v[196:199], v[0:3]
	s_add_i32 s58, 0, 0x18000
	v_add_u32_e32 v164, s58, v145
	s_barrier
	s_branch .Lg131_mid
.LBB0_131:
	s_add_u32 s26, s20, 0xfffc0080
	s_addc_u32 s27, s21, -1
	s_cmp_eq_u32 s57, 12
	s_cselect_b32 s29, s13, s27
	s_cselect_b32 s28, s53, s26
	s_cselect_b32 s27, s11, s56
	s_cselect_b32 s26, s54, s55
	s_add_i32 m0, s19, 0xc000
	s_nop 0
	global_load_lds_dwordx4 v136, s[20:21]
	s_add_i32 m0, s19, 0xe000
	s_nop 0
	global_load_lds_dwordx4 v138, s[20:21]
	ds_read_b128 v[152:155], v149
	ds_read_b128 v[156:159], v149 offset:1024
	ds_read_b128 v[160:163], v149 offset:2048
	ds_read_b128 v[164:167], v149 offset:3072
	ds_read_b128 v[168:171], v150
	ds_read_b128 v[172:175], v150 offset:1024
	ds_read_b128 v[176:179], v150 offset:2048
	ds_read_b128 v[180:183], v150 offset:3072
	ds_read_b128 v[184:187], v150 offset:4096
	ds_read_b128 v[188:191], v150 offset:5120
	ds_read_b128 v[192:195], v150 offset:6144
	ds_read_b128 v[196:199], v150 offset:7168
	s_waitcnt lgkmcnt(8)
	s_barrier
	s_waitcnt lgkmcnt(0)
	s_waitcnt lgkmcnt(0)
	v_mfma_f32_16x16x32_bf16 v[124:127], v[152:155], v[168:171], v[124:127]
	v_mfma_f32_16x16x32_bf16 v[120:123], v[160:163], v[168:171], v[120:123]
	v_mfma_f32_16x16x32_bf16 v[108:111], v[152:155], v[176:179], v[108:111]
	v_mfma_f32_16x16x32_bf16 v[104:107], v[160:163], v[176:179], v[104:107]
	v_mfma_f32_16x16x32_bf16 v[92:95], v[152:155], v[184:187], v[92:95]
	v_mfma_f32_16x16x32_bf16 v[88:91], v[160:163], v[184:187], v[88:91]
	v_mfma_f32_16x16x32_bf16 v[76:79], v[152:155], v[192:195], v[76:79]
	v_mfma_f32_16x16x32_bf16 v[72:75], v[160:163], v[192:195], v[72:75]
	v_mfma_f32_16x16x32_bf16 v[124:127], v[156:159], v[172:175], v[124:127]
	v_mfma_f32_16x16x32_bf16 v[120:123], v[164:167], v[172:175], v[120:123]
	v_mfma_f32_16x16x32_bf16 v[108:111], v[156:159], v[180:183], v[108:111]
	v_mfma_f32_16x16x32_bf16 v[104:107], v[164:167], v[180:183], v[104:107]
	v_mfma_f32_16x16x32_bf16 v[92:95], v[156:159], v[188:191], v[92:95]
	v_mfma_f32_16x16x32_bf16 v[88:91], v[164:167], v[188:191], v[88:91]
	v_mfma_f32_16x16x32_bf16 v[76:79], v[156:159], v[196:199], v[76:79]
	v_mfma_f32_16x16x32_bf16 v[72:75], v[164:167], v[196:199], v[72:75]
	s_barrier
	s_add_i32 s58, s47, s38
	s_add_u32 s80, s26, 0x80
	s_addc_u32 s81, s27, 0
	s_mov_b32 m0, s58
	s_nop 0
	global_load_lds_dwordx4 v132, s[26:27]
	s_add_i32 m0, s58, 0x2000
	s_nop 0
	global_load_lds_dwordx4 v128, s[26:27]
	ds_read_b128 v[200:203], v151
	ds_read_b128 v[204:207], v151 offset:1024
	ds_read_b128 v[208:211], v151 offset:2048
	ds_read_b128 v[212:215], v151 offset:3072
	s_waitcnt vmcnt(10)
	s_barrier
	s_waitcnt lgkmcnt(0)
	s_waitcnt lgkmcnt(0)
	v_mfma_f32_16x16x32_bf16 v[116:119], v[200:203], v[168:171], v[116:119]
	v_mfma_f32_16x16x32_bf16 v[112:115], v[208:211], v[168:171], v[112:115]
	v_mfma_f32_16x16x32_bf16 v[100:103], v[200:203], v[176:179], v[100:103]
	v_mfma_f32_16x16x32_bf16 v[96:99], v[208:211], v[176:179], v[96:99]
	v_mfma_f32_16x16x32_bf16 v[84:87], v[200:203], v[184:187], v[84:87]
	v_mfma_f32_16x16x32_bf16 v[80:83], v[208:211], v[184:187], v[80:83]
	v_mfma_f32_16x16x32_bf16 v[68:71], v[200:203], v[192:195], v[68:71]
	v_mfma_f32_16x16x32_bf16 v[64:67], v[208:211], v[192:195], v[64:67]
	v_mfma_f32_16x16x32_bf16 v[116:119], v[204:207], v[172:175], v[116:119]
	v_mfma_f32_16x16x32_bf16 v[112:115], v[212:215], v[172:175], v[112:115]
	v_mfma_f32_16x16x32_bf16 v[100:103], v[204:207], v[180:183], v[100:103]
	v_mfma_f32_16x16x32_bf16 v[96:99], v[212:215], v[180:183], v[96:99]
	v_mfma_f32_16x16x32_bf16 v[84:87], v[204:207], v[188:191], v[84:87]
	v_mfma_f32_16x16x32_bf16 v[80:83], v[212:215], v[188:191], v[80:83]
	v_mfma_f32_16x16x32_bf16 v[68:71], v[204:207], v[196:199], v[68:71]
	v_mfma_f32_16x16x32_bf16 v[64:67], v[212:215], v[196:199], v[64:67]
	s_mov_b32 m0, s19
	s_add_u32 s82, s28, 0x80
	s_addc_u32 s83, s29, 0
	s_barrier
	global_load_lds_dwordx4 v134, s[28:29]
	s_mov_b32 m0, s42
	s_nop 0
	global_load_lds_dwordx4 v130, s[28:29]
	ds_read_b128 v[168:171], v150 offset:16384
	ds_read_b128 v[172:175], v150 offset:17408
	ds_read_b128 v[176:179], v150 offset:18432
	ds_read_b128 v[180:183], v150 offset:19456
	ds_read_b128 v[184:187], v150 offset:20480
	ds_read_b128 v[188:191], v150 offset:21504
	ds_read_b128 v[192:195], v150 offset:22528
	ds_read_b128 v[196:199], v150 offset:23552
	s_barrier
	s_waitcnt lgkmcnt(0)
	s_waitcnt lgkmcnt(0)
	v_mfma_f32_16x16x32_bf16 v[60:63], v[152:155], v[168:171], v[60:63]
	v_mfma_f32_16x16x32_bf16 v[56:59], v[160:163], v[168:171], v[56:59]
	v_mfma_f32_16x16x32_bf16 v[44:47], v[152:155], v[176:179], v[44:47]
	v_mfma_f32_16x16x32_bf16 v[40:43], v[160:163], v[176:179], v[40:43]
	v_mfma_f32_16x16x32_bf16 v[28:31], v[152:155], v[184:187], v[28:31]
	v_mfma_f32_16x16x32_bf16 v[24:27], v[160:163], v[184:187], v[24:27]
	v_mfma_f32_16x16x32_bf16 v[12:15], v[152:155], v[192:195], v[12:15]
	v_mfma_f32_16x16x32_bf16 v[8:11], v[160:163], v[192:195], v[8:11]
	v_mfma_f32_16x16x32_bf16 v[60:63], v[156:159], v[172:175], v[60:63]
	v_mfma_f32_16x16x32_bf16 v[56:59], v[164:167], v[172:175], v[56:59]
	v_mfma_f32_16x16x32_bf16 v[44:47], v[156:159], v[180:183], v[44:47]
	v_mfma_f32_16x16x32_bf16 v[40:43], v[164:167], v[180:183], v[40:43]
	v_mfma_f32_16x16x32_bf16 v[28:31], v[156:159], v[188:191], v[28:31]
	v_mfma_f32_16x16x32_bf16 v[24:27], v[164:167], v[188:191], v[24:27]
	v_mfma_f32_16x16x32_bf16 v[12:15], v[156:159], v[196:199], v[12:15]
	v_mfma_f32_16x16x32_bf16 v[8:11], v[164:167], v[196:199], v[8:11]
	s_barrier
	s_add_u32 s58, s26, 0x40000
	s_addc_u32 s59, s27, 0
	s_add_i32 s60, s48, s38
	s_mov_b32 m0, s60
	s_nop 0
	global_load_lds_dwordx4 v132, s[58:59]
	s_add_i32 m0, s60, 0x2000
	s_nop 0
	global_load_lds_dwordx4 v128, s[58:59]
	s_waitcnt vmcnt(8)
	s_barrier
	v_mfma_f32_16x16x32_bf16 v[52:55], v[200:203], v[168:171], v[52:55]
	v_mfma_f32_16x16x32_bf16 v[48:51], v[208:211], v[168:171], v[48:51]
	v_mfma_f32_16x16x32_bf16 v[36:39], v[200:203], v[176:179], v[36:39]
	v_mfma_f32_16x16x32_bf16 v[32:35], v[208:211], v[176:179], v[32:35]
	v_mfma_f32_16x16x32_bf16 v[20:23], v[200:203], v[184:187], v[20:23]
	v_mfma_f32_16x16x32_bf16 v[16:19], v[208:211], v[184:187], v[16:19]
	v_mfma_f32_16x16x32_bf16 v[4:7], v[200:203], v[192:195], v[4:7]
	v_mfma_f32_16x16x32_bf16 v[0:3], v[208:211], v[192:195], v[0:3]
	v_mfma_f32_16x16x32_bf16 v[52:55], v[204:207], v[172:175], v[52:55]
	v_mfma_f32_16x16x32_bf16 v[48:51], v[212:215], v[172:175], v[48:51]
	v_mfma_f32_16x16x32_bf16 v[36:39], v[204:207], v[180:183], v[36:39]
	v_mfma_f32_16x16x32_bf16 v[32:35], v[212:215], v[180:183], v[32:35]
	v_mfma_f32_16x16x32_bf16 v[20:23], v[204:207], v[188:191], v[20:23]
	v_mfma_f32_16x16x32_bf16 v[16:19], v[212:215], v[188:191], v[16:19]
	v_mfma_f32_16x16x32_bf16 v[4:7], v[204:207], v[196:199], v[4:7]
	v_mfma_f32_16x16x32_bf16 v[0:3], v[212:215], v[196:199], v[0:3]
	s_add_i32 s58, 0, 0x18000
	v_add_u32_e32 v164, s58, v145
	s_barrier
.Lg131_mid:
	s_add_u32 s28, s28, 0x40000
	s_addc_u32 s29, s29, 0
	s_mov_b32 m0, s43
	s_nop 0
	global_load_lds_dwordx4 v134, s[28:29]
	s_mov_b32 m0, s44
	s_nop 0
	global_load_lds_dwordx4 v130, s[28:29]
	ds_read_b128 v[152:155], v164
	ds_read_b128 v[156:159], v164 offset:1024
	ds_read_b128 v[160:163], v164 offset:2048
	ds_read_b128 v[164:167], v164 offset:3072
	ds_read_b128 v[168:171], v150 offset:32768
	ds_read_b128 v[172:175], v150 offset:33792
	ds_read_b128 v[176:179], v150 offset:34816
	ds_read_b128 v[180:183], v150 offset:35840
	ds_read_b128 v[184:187], v150 offset:36864
	ds_read_b128 v[188:191], v150 offset:37888
	ds_read_b128 v[192:195], v150 offset:38912
	ds_read_b128 v[196:199], v150 offset:39936
	s_waitcnt lgkmcnt(8)
	s_barrier
	s_waitcnt lgkmcnt(0)
	s_waitcnt lgkmcnt(0)
	v_mfma_f32_16x16x32_bf16 v[124:127], v[152:155], v[168:171], v[124:127]
	v_mfma_f32_16x16x32_bf16 v[120:123], v[160:163], v[168:171], v[120:123]
	v_mfma_f32_16x16x32_bf16 v[108:111], v[152:155], v[176:179], v[108:111]
	v_mfma_f32_16x16x32_bf16 v[104:107], v[160:163], v[176:179], v[104:107]
	v_mfma_f32_16x16x32_bf16 v[92:95], v[152:155], v[184:187], v[92:95]
	v_mfma_f32_16x16x32_bf16 v[88:91], v[160:163], v[184:187], v[88:91]
	v_mfma_f32_16x16x32_bf16 v[76:79], v[152:155], v[192:195], v[76:79]
	v_mfma_f32_16x16x32_bf16 v[72:75], v[160:163], v[192:195], v[72:75]
	v_mfma_f32_16x16x32_bf16 v[124:127], v[156:159], v[172:175], v[124:127]
	v_mfma_f32_16x16x32_bf16 v[120:123], v[164:167], v[172:175], v[120:123]
	v_mfma_f32_16x16x32_bf16 v[108:111], v[156:159], v[180:183], v[108:111]
	v_mfma_f32_16x16x32_bf16 v[104:107], v[164:167], v[180:183], v[104:107]
	v_mfma_f32_16x16x32_bf16 v[92:95], v[156:159], v[188:191], v[92:95]
	v_mfma_f32_16x16x32_bf16 v[88:91], v[164:167], v[188:191], v[88:91]
	v_mfma_f32_16x16x32_bf16 v[76:79], v[156:159], v[196:199], v[76:79]
	v_mfma_f32_16x16x32_bf16 v[72:75], v[164:167], v[196:199], v[72:75]
	s_barrier
	s_add_i32 s28, 0, 0x1c000
	s_add_i32 s29, s58, s38
	v_add_u32_e32 v212, s28, v145
	s_mov_b32 m0, s29
	s_nop 0
	global_load_lds_dwordx4 v132, s[80:81]
	s_add_i32 m0, s29, 0x2000
	s_nop 0
	global_load_lds_dwordx4 v128, s[80:81]
	ds_read_b128 v[200:203], v212
	ds_read_b128 v[204:207], v212 offset:1024
	ds_read_b128 v[208:211], v212 offset:2048
	ds_read_b128 v[212:215], v212 offset:3072
	s_waitcnt vmcnt(10)
	s_barrier
	s_waitcnt lgkmcnt(0)
	s_waitcnt lgkmcnt(0)
	v_mfma_f32_16x16x32_bf16 v[116:119], v[200:203], v[168:171], v[116:119]
	v_mfma_f32_16x16x32_bf16 v[112:115], v[208:211], v[168:171], v[112:115]
	v_mfma_f32_16x16x32_bf16 v[100:103], v[200:203], v[176:179], v[100:103]
	v_mfma_f32_16x16x32_bf16 v[96:99], v[208:211], v[176:179], v[96:99]
	v_mfma_f32_16x16x32_bf16 v[84:87], v[200:203], v[184:187], v[84:87]
	v_mfma_f32_16x16x32_bf16 v[80:83], v[208:211], v[184:187], v[80:83]
	v_mfma_f32_16x16x32_bf16 v[68:71], v[200:203], v[192:195], v[68:71]
	v_mfma_f32_16x16x32_bf16 v[64:67], v[208:211], v[192:195], v[64:67]
	v_mfma_f32_16x16x32_bf16 v[116:119], v[204:207], v[172:175], v[116:119]
	v_mfma_f32_16x16x32_bf16 v[112:115], v[212:215], v[172:175], v[112:115]
	v_mfma_f32_16x16x32_bf16 v[100:103], v[204:207], v[180:183], v[100:103]
	v_mfma_f32_16x16x32_bf16 v[96:99], v[212:215], v[180:183], v[96:99]
	v_mfma_f32_16x16x32_bf16 v[84:87], v[204:207], v[188:191], v[84:87]
	v_mfma_f32_16x16x32_bf16 v[80:83], v[212:215], v[188:191], v[80:83]
	v_mfma_f32_16x16x32_bf16 v[68:71], v[204:207], v[196:199], v[68:71]
	v_mfma_f32_16x16x32_bf16 v[64:67], v[212:215], v[196:199], v[64:67]
	s_mov_b32 m0, s45
	s_barrier
	global_load_lds_dwordx4 v134, s[82:83]
	s_mov_b32 m0, s46
	s_nop 0
	global_load_lds_dwordx4 v130, s[82:83]
	ds_read_b128 v[168:171], v150 offset:49152
	ds_read_b128 v[172:175], v150 offset:50176
	ds_read_b128 v[176:179], v150 offset:51200
	ds_read_b128 v[180:183], v150 offset:52224
	ds_read_b128 v[184:187], v150 offset:53248
	ds_read_b128 v[188:191], v150 offset:54272
	ds_read_b128 v[192:195], v150 offset:55296
	ds_read_b128 v[196:199], v150 offset:56320
	s_barrier
	s_waitcnt lgkmcnt(0)
	s_waitcnt lgkmcnt(0)
	v_mfma_f32_16x16x32_bf16 v[60:63], v[152:155], v[168:171], v[60:63]
	v_mfma_f32_16x16x32_bf16 v[56:59], v[160:163], v[168:171], v[56:59]
	v_mfma_f32_16x16x32_bf16 v[44:47], v[152:155], v[176:179], v[44:47]
	v_mfma_f32_16x16x32_bf16 v[40:43], v[160:163], v[176:179], v[40:43]
	v_mfma_f32_16x16x32_bf16 v[28:31], v[152:155], v[184:187], v[28:31]
	v_mfma_f32_16x16x32_bf16 v[24:27], v[160:163], v[184:187], v[24:27]
	v_mfma_f32_16x16x32_bf16 v[12:15], v[152:155], v[192:195], v[12:15]
	v_mfma_f32_16x16x32_bf16 v[8:11], v[160:163], v[192:195], v[8:11]
	v_mfma_f32_16x16x32_bf16 v[60:63], v[156:159], v[172:175], v[60:63]
	v_mfma_f32_16x16x32_bf16 v[56:59], v[164:167], v[172:175], v[56:59]
	v_mfma_f32_16x16x32_bf16 v[44:47], v[156:159], v[180:183], v[44:47]
	v_mfma_f32_16x16x32_bf16 v[40:43], v[164:167], v[180:183], v[40:43]
	v_mfma_f32_16x16x32_bf16 v[28:31], v[156:159], v[188:191], v[28:31]
	v_mfma_f32_16x16x32_bf16 v[24:27], v[164:167], v[188:191], v[24:27]
	v_mfma_f32_16x16x32_bf16 v[12:15], v[156:159], v[196:199], v[12:15]
	v_mfma_f32_16x16x32_bf16 v[8:11], v[164:167], v[196:199], v[8:11]
	s_barrier
	s_add_u32 s26, s26, 0x40080
	s_addc_u32 s27, s27, 0
	s_add_i32 s28, s28, s38
	s_mov_b32 m0, s28
	s_nop 0
	global_load_lds_dwordx4 v132, s[26:27]
	s_add_i32 m0, s28, 0x2000
	s_nop 0
	global_load_lds_dwordx4 v128, s[26:27]
	s_waitcnt vmcnt(8)
	s_barrier
	v_mfma_f32_16x16x32_bf16 v[52:55], v[200:203], v[168:171], v[52:55]
	v_mfma_f32_16x16x32_bf16 v[48:51], v[208:211], v[168:171], v[48:51]
	v_mfma_f32_16x16x32_bf16 v[36:39], v[200:203], v[176:179], v[36:39]
	v_mfma_f32_16x16x32_bf16 v[32:35], v[208:211], v[176:179], v[32:35]
	v_mfma_f32_16x16x32_bf16 v[20:23], v[200:203], v[184:187], v[20:23]
	v_mfma_f32_16x16x32_bf16 v[16:19], v[208:211], v[184:187], v[16:19]
	v_mfma_f32_16x16x32_bf16 v[4:7], v[200:203], v[192:195], v[4:7]
	v_mfma_f32_16x16x32_bf16 v[0:3], v[208:211], v[192:195], v[0:3]
	v_mfma_f32_16x16x32_bf16 v[52:55], v[204:207], v[172:175], v[52:55]
	v_mfma_f32_16x16x32_bf16 v[48:51], v[212:215], v[172:175], v[48:51]
	v_mfma_f32_16x16x32_bf16 v[36:39], v[204:207], v[180:183], v[36:39]
	v_mfma_f32_16x16x32_bf16 v[32:35], v[212:215], v[180:183], v[32:35]
	v_mfma_f32_16x16x32_bf16 v[20:23], v[204:207], v[188:191], v[20:23]
	v_mfma_f32_16x16x32_bf16 v[16:19], v[212:215], v[188:191], v[16:19]
	v_mfma_f32_16x16x32_bf16 v[4:7], v[204:207], v[196:199], v[4:7]
	v_mfma_f32_16x16x32_bf16 v[0:3], v[212:215], v[196:199], v[0:3]
	s_add_i32 s57, s57, 2
	s_add_u32 s20, s20, 0x100
	s_addc_u32 s21, s21, 0
	s_add_u32 s55, s55, 0x100
	s_addc_u32 s56, s56, 0
	s_cmp_gt_u32 s57, 13
	s_barrier
	s_cbranch_scc0 .LBB0_131
	s_setprio 0
	s_cmpk_gt_u32 s37, 0xff
	s_cbranch_scc1 .Lg131_nox
	s_barrier
	s_setprio 1

.Lg248_noy:
	s_add_u32 s26, s20, 0x100
	s_addc_u32 s27, s21, 0
	s_cmp_eq_u32 s59, 40
	s_cselect_b32 s31, s9, s27
	s_cselect_b32 s30, s8, s26
	s_cselect_b32 s29, s11, s58
	s_cselect_b32 s28, s10, s57
	s_add_i32 m0, s41, 0xc000
	s_nop 0
	global_load_lds_dwordx4 v136, s[20:21]
	s_add_i32 m0, s41, 0xe000
	s_nop 0
	global_load_lds_dwordx4 v138, s[20:21]
	ds_read_b128 v[144:147], v151
	ds_read_b128 v[156:159], v151 offset:1024
	ds_read_b128 v[160:163], v151 offset:2048
	ds_read_b128 v[164:167], v151 offset:3072
	ds_read_b128 v[168:171], v152
	ds_read_b128 v[172:175], v152 offset:1024
	ds_read_b128 v[176:179], v152 offset:2048
	ds_read_b128 v[180:183], v152 offset:3072
	ds_read_b128 v[184:187], v152 offset:4096
	ds_read_b128 v[188:191], v152 offset:5120
	ds_read_b128 v[192:195], v152 offset:6144
	ds_read_b128 v[196:199], v152 offset:7168
	s_waitcnt lgkmcnt(8)
	s_barrier
	s_waitcnt lgkmcnt(0)
	s_waitcnt lgkmcnt(0)
	v_mfma_f32_16x16x32_bf16 v[124:127], v[144:147], v[168:171], 0
	v_mfma_f32_16x16x32_bf16 v[120:123], v[160:163], v[168:171], 0
	v_mfma_f32_16x16x32_bf16 v[108:111], v[144:147], v[176:179], 0
	v_mfma_f32_16x16x32_bf16 v[104:107], v[160:163], v[176:179], 0
	v_mfma_f32_16x16x32_bf16 v[92:95], v[144:147], v[184:187], 0
	v_mfma_f32_16x16x32_bf16 v[88:91], v[160:163], v[184:187], 0
	v_mfma_f32_16x16x32_bf16 v[76:79], v[144:147], v[192:195], 0
	v_mfma_f32_16x16x32_bf16 v[72:75], v[160:163], v[192:195], 0
	v_mfma_f32_16x16x32_bf16 v[124:127], v[156:159], v[172:175], v[124:127]
	v_mfma_f32_16x16x32_bf16 v[120:123], v[164:167], v[172:175], v[120:123]
	v_mfma_f32_16x16x32_bf16 v[108:111], v[156:159], v[180:183], v[108:111]
	v_mfma_f32_16x16x32_bf16 v[104:107], v[164:167], v[180:183], v[104:107]
	v_mfma_f32_16x16x32_bf16 v[92:95], v[156:159], v[188:191], v[92:95]
	v_mfma_f32_16x16x32_bf16 v[88:91], v[164:167], v[188:191], v[88:91]
	v_mfma_f32_16x16x32_bf16 v[76:79], v[156:159], v[196:199], v[76:79]
	v_mfma_f32_16x16x32_bf16 v[72:75], v[164:167], v[196:199], v[72:75]
	s_barrier
	s_add_i32 s20, s51, s40
	s_add_u32 s80, s28, 0x80
	s_addc_u32 s81, s29, 0
	s_mov_b32 m0, s20
	s_nop 0
	global_load_lds_dwordx4 v130, s[28:29]
	s_add_i32 m0, s20, 0x2000
	s_nop 0
	global_load_lds_dwordx4 v134, s[28:29]
	ds_read_b128 v[200:203], v153
	ds_read_b128 v[204:207], v153 offset:1024
	ds_read_b128 v[208:211], v153 offset:2048
	ds_read_b128 v[212:215], v153 offset:3072
	s_waitcnt vmcnt(10)
	s_barrier
	s_waitcnt lgkmcnt(0)
	s_waitcnt lgkmcnt(0)
	v_mfma_f32_16x16x32_bf16 v[116:119], v[200:203], v[168:171], 0
	v_mfma_f32_16x16x32_bf16 v[112:115], v[208:211], v[168:171], 0
	v_mfma_f32_16x16x32_bf16 v[100:103], v[200:203], v[176:179], 0
	v_mfma_f32_16x16x32_bf16 v[96:99], v[208:211], v[176:179], 0
	v_mfma_f32_16x16x32_bf16 v[84:87], v[200:203], v[184:187], 0
	v_mfma_f32_16x16x32_bf16 v[80:83], v[208:211], v[184:187], 0
	v_mfma_f32_16x16x32_bf16 v[68:71], v[200:203], v[192:195], 0
	v_mfma_f32_16x16x32_bf16 v[64:67], v[208:211], v[192:195], 0
	v_mfma_f32_16x16x32_bf16 v[116:119], v[204:207], v[172:175], v[116:119]
	v_mfma_f32_16x16x32_bf16 v[112:115], v[212:215], v[172:175], v[112:115]
	v_mfma_f32_16x16x32_bf16 v[100:103], v[204:207], v[180:183], v[100:103]
	v_mfma_f32_16x16x32_bf16 v[96:99], v[212:215], v[180:183], v[96:99]
	v_mfma_f32_16x16x32_bf16 v[84:87], v[204:207], v[188:191], v[84:87]
	v_mfma_f32_16x16x32_bf16 v[80:83], v[212:215], v[188:191], v[80:83]
	v_mfma_f32_16x16x32_bf16 v[68:71], v[204:207], v[196:199], v[68:71]
	v_mfma_f32_16x16x32_bf16 v[64:67], v[212:215], v[196:199], v[64:67]
	s_mov_b32 m0, s41
	s_add_u32 s82, s30, 0x80
	s_addc_u32 s83, s31, 0
	s_barrier
	global_load_lds_dwordx4 v128, s[30:31]
	s_mov_b32 m0, s42
	s_nop 0
	global_load_lds_dwordx4 v132, s[30:31]
	ds_read_b128 v[168:171], v152 offset:16384
	ds_read_b128 v[172:175], v152 offset:17408
	ds_read_b128 v[176:179], v152 offset:18432
	ds_read_b128 v[180:183], v152 offset:19456
	ds_read_b128 v[184:187], v152 offset:20480
	ds_read_b128 v[188:191], v152 offset:21504
	ds_read_b128 v[192:195], v152 offset:22528
	ds_read_b128 v[196:199], v152 offset:23552
	s_barrier
	s_waitcnt lgkmcnt(0)
	s_waitcnt lgkmcnt(0)
	v_mfma_f32_16x16x32_bf16 v[60:63], v[144:147], v[168:171], 0
	v_mfma_f32_16x16x32_bf16 v[56:59], v[160:163], v[168:171], 0
	v_mfma_f32_16x16x32_bf16 v[44:47], v[144:147], v[176:179], 0
	v_mfma_f32_16x16x32_bf16 v[40:43], v[160:163], v[176:179], 0
	v_mfma_f32_16x16x32_bf16 v[28:31], v[144:147], v[184:187], 0
	v_mfma_f32_16x16x32_bf16 v[24:27], v[160:163], v[184:187], 0
	v_mfma_f32_16x16x32_bf16 v[12:15], v[144:147], v[192:195], 0
	v_mfma_f32_16x16x32_bf16 v[8:11], v[160:163], v[192:195], 0
	v_mfma_f32_16x16x32_bf16 v[60:63], v[156:159], v[172:175], v[60:63]
	v_mfma_f32_16x16x32_bf16 v[56:59], v[164:167], v[172:175], v[56:59]
	v_mfma_f32_16x16x32_bf16 v[44:47], v[156:159], v[180:183], v[44:47]
	v_mfma_f32_16x16x32_bf16 v[40:43], v[164:167], v[180:183], v[40:43]
	v_mfma_f32_16x16x32_bf16 v[28:31], v[156:159], v[188:191], v[28:31]
	v_mfma_f32_16x16x32_bf16 v[24:27], v[164:167], v[188:191], v[24:27]
	v_mfma_f32_16x16x32_bf16 v[12:15], v[156:159], v[196:199], v[12:15]
	v_mfma_f32_16x16x32_bf16 v[8:11], v[164:167], v[196:199], v[8:11]
	s_barrier
	s_add_u32 s20, s28, 0xb0000
	s_addc_u32 s21, s29, 0
	s_add_i32 s60, s52, s40
	s_mov_b32 m0, s60
	s_nop 0
	global_load_lds_dwordx4 v130, s[20:21]
	s_add_i32 m0, s60, 0x2000
	s_nop 0
	global_load_lds_dwordx4 v134, s[20:21]
	s_waitcnt vmcnt(8)
	s_barrier
	v_mfma_f32_16x16x32_bf16 v[52:55], v[200:203], v[168:171], 0
	v_mfma_f32_16x16x32_bf16 v[48:51], v[208:211], v[168:171], 0
	v_mfma_f32_16x16x32_bf16 v[36:39], v[200:203], v[176:179], 0
	v_mfma_f32_16x16x32_bf16 v[32:35], v[208:211], v[176:179], 0
	v_mfma_f32_16x16x32_bf16 v[20:23], v[200:203], v[184:187], 0
	v_mfma_f32_16x16x32_bf16 v[16:19], v[208:211], v[184:187], 0
	v_mfma_f32_16x16x32_bf16 v[4:7], v[200:203], v[192:195], 0
	v_mfma_f32_16x16x32_bf16 v[0:3], v[208:211], v[192:195], 0
	v_mfma_f32_16x16x32_bf16 v[52:55], v[204:207], v[172:175], v[52:55]
	v_mfma_f32_16x16x32_bf16 v[48:51], v[212:215], v[172:175], v[48:51]
	v_mfma_f32_16x16x32_bf16 v[36:39], v[204:207], v[180:183], v[36:39]
	v_mfma_f32_16x16x32_bf16 v[32:35], v[212:215], v[180:183], v[32:35]
	v_mfma_f32_16x16x32_bf16 v[20:23], v[204:207], v[188:191], v[20:23]
	v_mfma_f32_16x16x32_bf16 v[16:19], v[212:215], v[188:191], v[16:19]
	v_mfma_f32_16x16x32_bf16 v[4:7], v[204:207], v[196:199], v[4:7]
	v_mfma_f32_16x16x32_bf16 v[0:3], v[212:215], v[196:199], v[0:3]
	s_add_i32 s60, 0, 0x18000
	v_add_u32_e32 v155, s60, v149
	s_barrier
	s_branch .Lg248_mid
.LBB0_248:
	s_add_u32 s26, s20, 0x100
	s_addc_u32 s27, s21, 0
	s_cmp_eq_u32 s59, 40
	s_cselect_b32 s31, s9, s27
	s_cselect_b32 s30, s8, s26
	s_cselect_b32 s29, s11, s58
	s_cselect_b32 s28, s10, s57
	s_add_i32 m0, s41, 0xc000
	s_nop 0
	global_load_lds_dwordx4 v136, s[20:21]
	s_add_i32 m0, s41, 0xe000
	s_nop 0
	global_load_lds_dwordx4 v138, s[20:21]
	ds_read_b128 v[144:147], v151
	ds_read_b128 v[156:159], v151 offset:1024
	ds_read_b128 v[160:163], v151 offset:2048
	ds_read_b128 v[164:167], v151 offset:3072
	ds_read_b128 v[168:171], v152
	ds_read_b128 v[172:175], v152 offset:1024
	ds_read_b128 v[176:179], v152 offset:2048
	ds_read_b128 v[180:183], v152 offset:3072
	ds_read_b128 v[184:187], v152 offset:4096
	ds_read_b128 v[188:191], v152 offset:5120
	ds_read_b128 v[192:195], v152 offset:6144
	ds_read_b128 v[196:199], v152 offset:7168
	s_waitcnt lgkmcnt(8)
	s_barrier
	s_waitcnt lgkmcnt(0)
	s_waitcnt lgkmcnt(0)
	v_mfma_f32_16x16x32_bf16 v[124:127], v[144:147], v[168:171], v[124:127]
	v_mfma_f32_16x16x32_bf16 v[120:123], v[160:163], v[168:171], v[120:123]
	v_mfma_f32_16x16x32_bf16 v[108:111], v[144:147], v[176:179], v[108:111]
	v_mfma_f32_16x16x32_bf16 v[104:107], v[160:163], v[176:179], v[104:107]
	v_mfma_f32_16x16x32_bf16 v[92:95], v[144:147], v[184:187], v[92:95]
	v_mfma_f32_16x16x32_bf16 v[88:91], v[160:163], v[184:187], v[88:91]
	v_mfma_f32_16x16x32_bf16 v[76:79], v[144:147], v[192:195], v[76:79]
	v_mfma_f32_16x16x32_bf16 v[72:75], v[160:163], v[192:195], v[72:75]
	v_mfma_f32_16x16x32_bf16 v[124:127], v[156:159], v[172:175], v[124:127]
	v_mfma_f32_16x16x32_bf16 v[120:123], v[164:167], v[172:175], v[120:123]
	v_mfma_f32_16x16x32_bf16 v[108:111], v[156:159], v[180:183], v[108:111]
	v_mfma_f32_16x16x32_bf16 v[104:107], v[164:167], v[180:183], v[104:107]
	v_mfma_f32_16x16x32_bf16 v[92:95], v[156:159], v[188:191], v[92:95]
	v_mfma_f32_16x16x32_bf16 v[88:91], v[164:167], v[188:191], v[88:91]
	v_mfma_f32_16x16x32_bf16 v[76:79], v[156:159], v[196:199], v[76:79]
	v_mfma_f32_16x16x32_bf16 v[72:75], v[164:167], v[196:199], v[72:75]
	s_barrier
	s_add_i32 s20, s51, s40
	s_add_u32 s80, s28, 0x80
	s_addc_u32 s81, s29, 0
	s_mov_b32 m0, s20
	s_nop 0
	global_load_lds_dwordx4 v130, s[28:29]
	s_add_i32 m0, s20, 0x2000
	s_nop 0
	global_load_lds_dwordx4 v134, s[28:29]
	ds_read_b128 v[200:203], v153
	ds_read_b128 v[204:207], v153 offset:1024
	ds_read_b128 v[208:211], v153 offset:2048
	ds_read_b128 v[212:215], v153 offset:3072
	s_waitcnt vmcnt(10)
	s_barrier
	s_waitcnt lgkmcnt(0)
	s_waitcnt lgkmcnt(0)
	v_mfma_f32_16x16x32_bf16 v[116:119], v[200:203], v[168:171], v[116:119]
	v_mfma_f32_16x16x32_bf16 v[112:115], v[208:211], v[168:171], v[112:115]
	v_mfma_f32_16x16x32_bf16 v[100:103], v[200:203], v[176:179], v[100:103]
	v_mfma_f32_16x16x32_bf16 v[96:99], v[208:211], v[176:179], v[96:99]
	v_mfma_f32_16x16x32_bf16 v[84:87], v[200:203], v[184:187], v[84:87]
	v_mfma_f32_16x16x32_bf16 v[80:83], v[208:211], v[184:187], v[80:83]
	v_mfma_f32_16x16x32_bf16 v[68:71], v[200:203], v[192:195], v[68:71]
	v_mfma_f32_16x16x32_bf16 v[64:67], v[208:211], v[192:195], v[64:67]
	v_mfma_f32_16x16x32_bf16 v[116:119], v[204:207], v[172:175], v[116:119]
	v_mfma_f32_16x16x32_bf16 v[112:115], v[212:215], v[172:175], v[112:115]
	v_mfma_f32_16x16x32_bf16 v[100:103], v[204:207], v[180:183], v[100:103]
	v_mfma_f32_16x16x32_bf16 v[96:99], v[212:215], v[180:183], v[96:99]
	v_mfma_f32_16x16x32_bf16 v[84:87], v[204:207], v[188:191], v[84:87]
	v_mfma_f32_16x16x32_bf16 v[80:83], v[212:215], v[188:191], v[80:83]
	v_mfma_f32_16x16x32_bf16 v[68:71], v[204:207], v[196:199], v[68:71]
	v_mfma_f32_16x16x32_bf16 v[64:67], v[212:215], v[196:199], v[64:67]
	s_mov_b32 m0, s41
	s_add_u32 s82, s30, 0x80
	s_addc_u32 s83, s31, 0
	s_barrier
	global_load_lds_dwordx4 v128, s[30:31]
	s_mov_b32 m0, s42
	s_nop 0
	global_load_lds_dwordx4 v132, s[30:31]
	ds_read_b128 v[168:171], v152 offset:16384
	ds_read_b128 v[172:175], v152 offset:17408
	ds_read_b128 v[176:179], v152 offset:18432
	ds_read_b128 v[180:183], v152 offset:19456
	ds_read_b128 v[184:187], v152 offset:20480
	ds_read_b128 v[188:191], v152 offset:21504
	ds_read_b128 v[192:195], v152 offset:22528
	ds_read_b128 v[196:199], v152 offset:23552
	s_barrier
	s_waitcnt lgkmcnt(0)
	s_waitcnt lgkmcnt(0)
	v_mfma_f32_16x16x32_bf16 v[60:63], v[144:147], v[168:171], v[60:63]
	v_mfma_f32_16x16x32_bf16 v[56:59], v[160:163], v[168:171], v[56:59]
	v_mfma_f32_16x16x32_bf16 v[44:47], v[144:147], v[176:179], v[44:47]
	v_mfma_f32_16x16x32_bf16 v[40:43], v[160:163], v[176:179], v[40:43]
	v_mfma_f32_16x16x32_bf16 v[28:31], v[144:147], v[184:187], v[28:31]
	v_mfma_f32_16x16x32_bf16 v[24:27], v[160:163], v[184:187], v[24:27]
	v_mfma_f32_16x16x32_bf16 v[12:15], v[144:147], v[192:195], v[12:15]
	v_mfma_f32_16x16x32_bf16 v[8:11], v[160:163], v[192:195], v[8:11]
	v_mfma_f32_16x16x32_bf16 v[60:63], v[156:159], v[172:175], v[60:63]
	v_mfma_f32_16x16x32_bf16 v[56:59], v[164:167], v[172:175], v[56:59]
	v_mfma_f32_16x16x32_bf16 v[44:47], v[156:159], v[180:183], v[44:47]
	v_mfma_f32_16x16x32_bf16 v[40:43], v[164:167], v[180:183], v[40:43]
	v_mfma_f32_16x16x32_bf16 v[28:31], v[156:159], v[188:191], v[28:31]
	v_mfma_f32_16x16x32_bf16 v[24:27], v[164:167], v[188:191], v[24:27]
	v_mfma_f32_16x16x32_bf16 v[12:15], v[156:159], v[196:199], v[12:15]
	v_mfma_f32_16x16x32_bf16 v[8:11], v[164:167], v[196:199], v[8:11]
	s_barrier
	s_add_u32 s20, s28, 0xb0000
	s_addc_u32 s21, s29, 0
	s_add_i32 s60, s52, s40
	s_mov_b32 m0, s60
	s_nop 0
	global_load_lds_dwordx4 v130, s[20:21]
	s_add_i32 m0, s60, 0x2000
	s_nop 0
	global_load_lds_dwordx4 v134, s[20:21]
	s_waitcnt vmcnt(8)
	s_barrier
	v_mfma_f32_16x16x32_bf16 v[52:55], v[200:203], v[168:171], v[52:55]
	v_mfma_f32_16x16x32_bf16 v[48:51], v[208:211], v[168:171], v[48:51]
	v_mfma_f32_16x16x32_bf16 v[36:39], v[200:203], v[176:179], v[36:39]
	v_mfma_f32_16x16x32_bf16 v[32:35], v[208:211], v[176:179], v[32:35]
	v_mfma_f32_16x16x32_bf16 v[20:23], v[200:203], v[184:187], v[20:23]
	v_mfma_f32_16x16x32_bf16 v[16:19], v[208:211], v[184:187], v[16:19]
	v_mfma_f32_16x16x32_bf16 v[4:7], v[200:203], v[192:195], v[4:7]
	v_mfma_f32_16x16x32_bf16 v[0:3], v[208:211], v[192:195], v[0:3]
	v_mfma_f32_16x16x32_bf16 v[52:55], v[204:207], v[172:175], v[52:55]
	v_mfma_f32_16x16x32_bf16 v[48:51], v[212:215], v[172:175], v[48:51]
	v_mfma_f32_16x16x32_bf16 v[36:39], v[204:207], v[180:183], v[36:39]
	v_mfma_f32_16x16x32_bf16 v[32:35], v[212:215], v[180:183], v[32:35]
	v_mfma_f32_16x16x32_bf16 v[20:23], v[204:207], v[188:191], v[20:23]
	v_mfma_f32_16x16x32_bf16 v[16:19], v[212:215], v[188:191], v[16:19]
	v_mfma_f32_16x16x32_bf16 v[4:7], v[204:207], v[196:199], v[4:7]
	v_mfma_f32_16x16x32_bf16 v[0:3], v[212:215], v[196:199], v[0:3]
	s_add_i32 s60, 0, 0x18000
	v_add_u32_e32 v155, s60, v149
	s_barrier
.Lg248_mid:
	s_add_u32 s20, s30, 0xb0000
	s_addc_u32 s21, s31, 0
	s_mov_b32 m0, s43
	s_nop 0
	global_load_lds_dwordx4 v128, s[20:21]
	s_mov_b32 m0, s44
	s_nop 0
	global_load_lds_dwordx4 v132, s[20:21]
	ds_read_b128 v[144:147], v155
	ds_read_b128 v[156:159], v155 offset:1024
	ds_read_b128 v[160:163], v155 offset:2048
	ds_read_b128 v[164:167], v155 offset:3072
	ds_read_b128 v[168:171], v152 offset:32768
	ds_read_b128 v[172:175], v152 offset:33792
	ds_read_b128 v[176:179], v152 offset:34816
	ds_read_b128 v[180:183], v152 offset:35840
	ds_read_b128 v[184:187], v152 offset:36864
	ds_read_b128 v[188:191], v152 offset:37888
	ds_read_b128 v[192:195], v152 offset:38912
	ds_read_b128 v[196:199], v152 offset:39936
	s_waitcnt lgkmcnt(8)
	s_barrier
	s_waitcnt lgkmcnt(0)
	s_waitcnt lgkmcnt(0)
	v_mfma_f32_16x16x32_bf16 v[124:127], v[144:147], v[168:171], v[124:127]
	v_mfma_f32_16x16x32_bf16 v[120:123], v[160:163], v[168:171], v[120:123]
	v_mfma_f32_16x16x32_bf16 v[108:111], v[144:147], v[176:179], v[108:111]
	v_mfma_f32_16x16x32_bf16 v[104:107], v[160:163], v[176:179], v[104:107]
	v_mfma_f32_16x16x32_bf16 v[92:95], v[144:147], v[184:187], v[92:95]
	v_mfma_f32_16x16x32_bf16 v[88:91], v[160:163], v[184:187], v[88:91]
	v_mfma_f32_16x16x32_bf16 v[76:79], v[144:147], v[192:195], v[76:79]
	v_mfma_f32_16x16x32_bf16 v[72:75], v[160:163], v[192:195], v[72:75]
	v_mfma_f32_16x16x32_bf16 v[124:127], v[156:159], v[172:175], v[124:127]
	v_mfma_f32_16x16x32_bf16 v[120:123], v[164:167], v[172:175], v[120:123]
	v_mfma_f32_16x16x32_bf16 v[108:111], v[156:159], v[180:183], v[108:111]
	v_mfma_f32_16x16x32_bf16 v[104:107], v[164:167], v[180:183], v[104:107]
	v_mfma_f32_16x16x32_bf16 v[92:95], v[156:159], v[188:191], v[92:95]
	v_mfma_f32_16x16x32_bf16 v[88:91], v[164:167], v[188:191], v[88:91]
	v_mfma_f32_16x16x32_bf16 v[76:79], v[156:159], v[196:199], v[76:79]
	v_mfma_f32_16x16x32_bf16 v[72:75], v[164:167], v[196:199], v[72:75]
	s_barrier
	s_add_i32 s30, 0, 0x1c000
	s_add_i32 s20, s60, s40
	v_add_u32_e32 v155, s30, v149
	s_mov_b32 m0, s20
	s_nop 0
	global_load_lds_dwordx4 v130, s[80:81]
	s_add_i32 m0, s20, 0x2000
	s_nop 0
	global_load_lds_dwordx4 v134, s[80:81]
	ds_read_b128 v[200:203], v155
	ds_read_b128 v[204:207], v155 offset:1024
	ds_read_b128 v[208:211], v155 offset:2048
	ds_read_b128 v[212:215], v155 offset:3072
	s_waitcnt vmcnt(10)
	s_barrier
	s_waitcnt lgkmcnt(0)
	s_waitcnt lgkmcnt(0)
	v_mfma_f32_16x16x32_bf16 v[116:119], v[200:203], v[168:171], v[116:119]
	v_mfma_f32_16x16x32_bf16 v[112:115], v[208:211], v[168:171], v[112:115]
	v_mfma_f32_16x16x32_bf16 v[100:103], v[200:203], v[176:179], v[100:103]
	v_mfma_f32_16x16x32_bf16 v[96:99], v[208:211], v[176:179], v[96:99]
	v_mfma_f32_16x16x32_bf16 v[84:87], v[200:203], v[184:187], v[84:87]
	v_mfma_f32_16x16x32_bf16 v[80:83], v[208:211], v[184:187], v[80:83]
	v_mfma_f32_16x16x32_bf16 v[68:71], v[200:203], v[192:195], v[68:71]
	v_mfma_f32_16x16x32_bf16 v[64:67], v[208:211], v[192:195], v[64:67]
	v_mfma_f32_16x16x32_bf16 v[116:119], v[204:207], v[172:175], v[116:119]
	v_mfma_f32_16x16x32_bf16 v[112:115], v[212:215], v[172:175], v[112:115]
	v_mfma_f32_16x16x32_bf16 v[100:103], v[204:207], v[180:183], v[100:103]
	v_mfma_f32_16x16x32_bf16 v[96:99], v[212:215], v[180:183], v[96:99]
	v_mfma_f32_16x16x32_bf16 v[84:87], v[204:207], v[188:191], v[84:87]
	v_mfma_f32_16x16x32_bf16 v[80:83], v[212:215], v[188:191], v[80:83]
	v_mfma_f32_16x16x32_bf16 v[68:71], v[204:207], v[196:199], v[68:71]
	v_mfma_f32_16x16x32_bf16 v[64:67], v[212:215], v[196:199], v[64:67]
	s_mov_b32 m0, s46
	s_barrier
	global_load_lds_dwordx4 v128, s[82:83]
	s_mov_b32 m0, s47
	s_nop 0
	global_load_lds_dwordx4 v132, s[82:83]
	ds_read_b128 v[168:171], v152 offset:49152
	ds_read_b128 v[172:175], v152 offset:50176
	ds_read_b128 v[176:179], v152 offset:51200
	ds_read_b128 v[180:183], v152 offset:52224
	ds_read_b128 v[184:187], v152 offset:53248
	ds_read_b128 v[188:191], v152 offset:54272
	ds_read_b128 v[192:195], v152 offset:55296
	ds_read_b128 v[196:199], v152 offset:56320
	s_barrier
	s_waitcnt lgkmcnt(0)
	s_waitcnt lgkmcnt(0)
	v_mfma_f32_16x16x32_bf16 v[60:63], v[144:147], v[168:171], v[60:63]
	v_mfma_f32_16x16x32_bf16 v[56:59], v[160:163], v[168:171], v[56:59]
	v_mfma_f32_16x16x32_bf16 v[44:47], v[144:147], v[176:179], v[44:47]
	v_mfma_f32_16x16x32_bf16 v[40:43], v[160:163], v[176:179], v[40:43]
	v_mfma_f32_16x16x32_bf16 v[28:31], v[144:147], v[184:187], v[28:31]
	v_mfma_f32_16x16x32_bf16 v[24:27], v[160:163], v[184:187], v[24:27]
	v_mfma_f32_16x16x32_bf16 v[12:15], v[144:147], v[192:195], v[12:15]
	v_mfma_f32_16x16x32_bf16 v[8:11], v[160:163], v[192:195], v[8:11]
	v_mfma_f32_16x16x32_bf16 v[60:63], v[156:159], v[172:175], v[60:63]
	v_mfma_f32_16x16x32_bf16 v[56:59], v[164:167], v[172:175], v[56:59]
	v_mfma_f32_16x16x32_bf16 v[44:47], v[156:159], v[180:183], v[44:47]
	v_mfma_f32_16x16x32_bf16 v[40:43], v[164:167], v[180:183], v[40:43]
	v_mfma_f32_16x16x32_bf16 v[28:31], v[156:159], v[188:191], v[28:31]
	v_mfma_f32_16x16x32_bf16 v[24:27], v[164:167], v[188:191], v[24:27]
	v_mfma_f32_16x16x32_bf16 v[12:15], v[156:159], v[196:199], v[12:15]
	v_mfma_f32_16x16x32_bf16 v[8:11], v[164:167], v[196:199], v[8:11]
	s_barrier
	s_add_u32 s20, s28, 0xb0080
	s_addc_u32 s21, s29, 0
	s_add_i32 s28, s30, s40
	s_mov_b32 m0, s28
	s_nop 0
	global_load_lds_dwordx4 v130, s[20:21]
	s_add_i32 m0, s28, 0x2000
	s_nop 0
	global_load_lds_dwordx4 v134, s[20:21]
	s_waitcnt vmcnt(8)
	s_barrier
	v_mfma_f32_16x16x32_bf16 v[52:55], v[200:203], v[168:171], v[52:55]
	v_mfma_f32_16x16x32_bf16 v[48:51], v[208:211], v[168:171], v[48:51]
	v_mfma_f32_16x16x32_bf16 v[36:39], v[200:203], v[176:179], v[36:39]
	v_mfma_f32_16x16x32_bf16 v[32:35], v[208:211], v[176:179], v[32:35]
	v_mfma_f32_16x16x32_bf16 v[20:23], v[200:203], v[184:187], v[20:23]
	v_mfma_f32_16x16x32_bf16 v[16:19], v[208:211], v[184:187], v[16:19]
	v_mfma_f32_16x16x32_bf16 v[4:7], v[200:203], v[192:195], v[4:7]
	v_mfma_f32_16x16x32_bf16 v[0:3], v[208:211], v[192:195], v[0:3]
	v_mfma_f32_16x16x32_bf16 v[52:55], v[204:207], v[172:175], v[52:55]
	v_mfma_f32_16x16x32_bf16 v[48:51], v[212:215], v[172:175], v[48:51]
	v_mfma_f32_16x16x32_bf16 v[36:39], v[204:207], v[180:183], v[36:39]
	v_mfma_f32_16x16x32_bf16 v[32:35], v[212:215], v[180:183], v[32:35]
	v_mfma_f32_16x16x32_bf16 v[20:23], v[204:207], v[188:191], v[20:23]
	v_mfma_f32_16x16x32_bf16 v[16:19], v[212:215], v[188:191], v[16:19]
	v_mfma_f32_16x16x32_bf16 v[4:7], v[204:207], v[196:199], v[4:7]
	v_mfma_f32_16x16x32_bf16 v[0:3], v[212:215], v[196:199], v[0:3]
	s_add_i32 s59, s59, 2
	s_add_u32 s57, s57, 0x100
	s_addc_u32 s58, s58, 0
	s_cmp_gt_u32 s59, 41
	s_mov_b64 s[20:21], s[26:27]
	s_barrier
	s_cbranch_scc0 .LBB0_248
	s_setprio 0
	v_lshl_add_u32 v146, s56, 8, v148
	v_ashrrev_i32_e32 v147, 31, v146
	v_lshl_or_b32 v144, s12, 8, v150
	v_lshlrev_b64 v[156:157], 11, v[146:147]
	v_ashrrev_i32_e32 v145, 31, v144
	v_lshl_add_u64 v[156:157], s[14:15], 0, v[156:157]
	v_lshl_add_u64 v[166:167], v[144:145], 1, v[156:157]
	global_load_dwordx4 v[158:161], v[166:167], off
	global_load_dwordx4 v[162:165], v[166:167], off offset:256
	s_mov_b64 s[84:85], 0x8000
	s_mov_b64 s[86:87], 0x28000
	v_lshl_add_u64 v[232:233], v[166:167], 0, s[84:85]
	global_load_dwordx4 v[176:179], v[232:233], off
	global_load_dwordx4 v[180:183], v[232:233], off offset:256
	v_lshl_add_u64 v[232:233], v[232:233], 0, s[84:85]
	global_load_dwordx4 v[184:187], v[232:233], off
	global_load_dwordx4 v[188:191], v[232:233], off offset:256
	v_lshl_add_u64 v[232:233], v[232:233], 0, s[84:85]
	global_load_dwordx4 v[192:195], v[232:233], off
	global_load_dwordx4 v[196:199], v[232:233], off offset:256
	v_lshl_add_u64 v[232:233], v[232:233], 0, s[86:87]
	global_load_dwordx4 v[200:203], v[232:233], off
	global_load_dwordx4 v[204:207], v[232:233], off offset:256
	v_lshl_add_u64 v[232:233], v[232:233], 0, s[84:85]
	global_load_dwordx4 v[208:211], v[232:233], off
	global_load_dwordx4 v[212:215], v[232:233], off offset:256
	v_lshl_add_u64 v[232:233], v[232:233], 0, s[84:85]
	global_load_dwordx4 v[216:219], v[232:233], off
	global_load_dwordx4 v[220:223], v[232:233], off offset:256
	v_lshl_add_u64 v[232:233], v[232:233], 0, s[84:85]
	global_load_dwordx4 v[224:227], v[232:233], off
	global_load_dwordx4 v[228:231], v[232:233], off offset:256
	s_cmpk_gt_u32 s35, 0xff
	s_cbranch_scc1 .Lg248_nox
	s_barrier
	s_setprio 1

.Lg359_noy:
	s_add_u32 s38, s8, 0xfffc0080
	s_addc_u32 s39, s9, -1
	s_cmp_eq_u32 s75, 12
	s_cselect_b32 s41, s21, s39
	s_cselect_b32 s40, s71, s38
	s_cselect_b32 s39, s19, s74
	s_cselect_b32 s38, s72, s73
	s_add_i32 m0, s37, 0xc000
	s_nop 0
	global_load_lds_dwordx4 v158, s[8:9]
	s_add_i32 m0, s37, 0xe000
	s_nop 0
	global_load_lds_dwordx4 v160, s[8:9]
	ds_read_b128 v[128:131], v181
	ds_read_b128 v[132:135], v181 offset:1024
	ds_read_b128 v[136:139], v181 offset:2048
	ds_read_b128 v[166:169], v181 offset:3072
	ds_read_b128 v[170:173], v182
	ds_read_b128 v[174:177], v182 offset:1024
	ds_read_b128 v[192:195], v182 offset:2048
	ds_read_b128 v[196:199], v182 offset:3072
	ds_read_b128 v[200:203], v182 offset:4096
	ds_read_b128 v[204:207], v182 offset:5120
	ds_read_b128 v[208:211], v182 offset:6144
	ds_read_b128 v[212:215], v182 offset:7168
	s_waitcnt lgkmcnt(8)
	s_barrier
	s_waitcnt lgkmcnt(0)
	s_waitcnt lgkmcnt(0)
	v_mfma_f32_16x16x32_bf16 v[124:127], v[128:131], v[170:173], 0
	v_mfma_f32_16x16x32_bf16 v[116:119], v[136:139], v[170:173], 0
	v_mfma_f32_16x16x32_bf16 v[108:111], v[128:131], v[192:195], 0
	v_mfma_f32_16x16x32_bf16 v[100:103], v[136:139], v[192:195], 0
	v_mfma_f32_16x16x32_bf16 v[92:95], v[128:131], v[200:203], 0
	v_mfma_f32_16x16x32_bf16 v[84:87], v[136:139], v[200:203], 0
	v_mfma_f32_16x16x32_bf16 v[76:79], v[128:131], v[208:211], 0
	v_mfma_f32_16x16x32_bf16 v[68:71], v[136:139], v[208:211], 0
	v_mfma_f32_16x16x32_bf16 v[124:127], v[132:135], v[174:177], v[124:127]
	v_mfma_f32_16x16x32_bf16 v[116:119], v[166:169], v[174:177], v[116:119]
	v_mfma_f32_16x16x32_bf16 v[108:111], v[132:135], v[196:199], v[108:111]
	v_mfma_f32_16x16x32_bf16 v[100:103], v[166:169], v[196:199], v[100:103]
	v_mfma_f32_16x16x32_bf16 v[92:95], v[132:135], v[204:207], v[92:95]
	v_mfma_f32_16x16x32_bf16 v[84:87], v[166:169], v[204:207], v[84:87]
	v_mfma_f32_16x16x32_bf16 v[76:79], v[132:135], v[212:215], v[76:79]
	v_mfma_f32_16x16x32_bf16 v[68:71], v[166:169], v[212:215], v[68:71]
	s_barrier
	s_add_i32 s76, s63, s46
	s_add_u32 s80, s38, 0x80
	s_addc_u32 s81, s39, 0
	s_mov_b32 m0, s76
	s_nop 0
	global_load_lds_dwordx4 v144, s[38:39]
	s_add_i32 m0, s76, 0x2000
	s_nop 0
	global_load_lds_dwordx4 v148, s[38:39]
	ds_read_b128 v[216:219], v183
	ds_read_b128 v[220:223], v183 offset:1024
	ds_read_b128 v[224:227], v183 offset:2048
	ds_read_b128 v[228:231], v183 offset:3072
	s_waitcnt vmcnt(10)
	s_barrier
	s_waitcnt lgkmcnt(0)
	s_waitcnt lgkmcnt(0)
	v_mfma_f32_16x16x32_bf16 v[120:123], v[216:219], v[170:173], 0
	v_mfma_f32_16x16x32_bf16 v[112:115], v[224:227], v[170:173], 0
	v_mfma_f32_16x16x32_bf16 v[104:107], v[216:219], v[192:195], 0
	v_mfma_f32_16x16x32_bf16 v[96:99], v[224:227], v[192:195], 0
	v_mfma_f32_16x16x32_bf16 v[88:91], v[216:219], v[200:203], 0
	v_mfma_f32_16x16x32_bf16 v[80:83], v[224:227], v[200:203], 0
	v_mfma_f32_16x16x32_bf16 v[72:75], v[216:219], v[208:211], 0
	v_mfma_f32_16x16x32_bf16 v[64:67], v[224:227], v[208:211], 0
	v_mfma_f32_16x16x32_bf16 v[120:123], v[220:223], v[174:177], v[120:123]
	v_mfma_f32_16x16x32_bf16 v[112:115], v[228:231], v[174:177], v[112:115]
	v_mfma_f32_16x16x32_bf16 v[104:107], v[220:223], v[196:199], v[104:107]
	v_mfma_f32_16x16x32_bf16 v[96:99], v[228:231], v[196:199], v[96:99]
	v_mfma_f32_16x16x32_bf16 v[88:91], v[220:223], v[204:207], v[88:91]
	v_mfma_f32_16x16x32_bf16 v[80:83], v[228:231], v[204:207], v[80:83]
	v_mfma_f32_16x16x32_bf16 v[72:75], v[220:223], v[212:215], v[72:75]
	v_mfma_f32_16x16x32_bf16 v[64:67], v[228:231], v[212:215], v[64:67]
	s_mov_b32 m0, s37
	s_add_u32 s82, s40, 0x80
	s_addc_u32 s83, s41, 0
	s_barrier
	global_load_lds_dwordx4 v142, s[40:41]
	s_mov_b32 m0, s51
	s_nop 0
	global_load_lds_dwordx4 v146, s[40:41]
	ds_read_b128 v[170:173], v182 offset:16384
	ds_read_b128 v[174:177], v182 offset:17408
	ds_read_b128 v[192:195], v182 offset:18432
	ds_read_b128 v[196:199], v182 offset:19456
	ds_read_b128 v[200:203], v182 offset:20480
	ds_read_b128 v[204:207], v182 offset:21504
	ds_read_b128 v[208:211], v182 offset:22528
	ds_read_b128 v[212:215], v182 offset:23552
	s_barrier
	s_waitcnt lgkmcnt(0)
	s_waitcnt lgkmcnt(0)
	v_mfma_f32_16x16x32_bf16 v[60:63], v[128:131], v[170:173], 0
	v_mfma_f32_16x16x32_bf16 v[52:55], v[136:139], v[170:173], 0
	v_mfma_f32_16x16x32_bf16 v[44:47], v[128:131], v[192:195], 0
	v_mfma_f32_16x16x32_bf16 v[36:39], v[136:139], v[192:195], 0
	v_mfma_f32_16x16x32_bf16 v[28:31], v[128:131], v[200:203], 0
	v_mfma_f32_16x16x32_bf16 v[20:23], v[136:139], v[200:203], 0
	v_mfma_f32_16x16x32_bf16 v[12:15], v[128:131], v[208:211], 0
	v_mfma_f32_16x16x32_bf16 v[4:7], v[136:139], v[208:211], 0
	v_mfma_f32_16x16x32_bf16 v[60:63], v[132:135], v[174:177], v[60:63]
	v_mfma_f32_16x16x32_bf16 v[52:55], v[166:169], v[174:177], v[52:55]
	v_mfma_f32_16x16x32_bf16 v[44:47], v[132:135], v[196:199], v[44:47]
	v_mfma_f32_16x16x32_bf16 v[36:39], v[166:169], v[196:199], v[36:39]
	v_mfma_f32_16x16x32_bf16 v[28:31], v[132:135], v[204:207], v[28:31]
	v_mfma_f32_16x16x32_bf16 v[20:23], v[166:169], v[204:207], v[20:23]
	v_mfma_f32_16x16x32_bf16 v[12:15], v[132:135], v[212:215], v[12:15]
	v_mfma_f32_16x16x32_bf16 v[4:7], v[166:169], v[212:215], v[4:7]
	s_barrier
	s_add_u32 s76, s38, 0x40000
	s_addc_u32 s77, s39, 0
	s_add_i32 s78, s64, s46
	s_mov_b32 m0, s78
	s_nop 0
	global_load_lds_dwordx4 v144, s[76:77]
	s_add_i32 m0, s78, 0x2000
	s_nop 0
	global_load_lds_dwordx4 v148, s[76:77]
	s_waitcnt vmcnt(8)
	s_barrier
	v_mfma_f32_16x16x32_bf16 v[56:59], v[216:219], v[170:173], 0
	v_mfma_f32_16x16x32_bf16 v[48:51], v[224:227], v[170:173], 0
	v_mfma_f32_16x16x32_bf16 v[40:43], v[216:219], v[192:195], 0
	v_mfma_f32_16x16x32_bf16 v[32:35], v[224:227], v[192:195], 0
	v_mfma_f32_16x16x32_bf16 v[24:27], v[216:219], v[200:203], 0
	v_mfma_f32_16x16x32_bf16 v[16:19], v[224:227], v[200:203], 0
	v_mfma_f32_16x16x32_bf16 v[8:11], v[216:219], v[208:211], 0
	v_mfma_f32_16x16x32_bf16 v[0:3], v[224:227], v[208:211], 0
	v_mfma_f32_16x16x32_bf16 v[56:59], v[220:223], v[174:177], v[56:59]
	v_mfma_f32_16x16x32_bf16 v[48:51], v[228:231], v[174:177], v[48:51]
	v_mfma_f32_16x16x32_bf16 v[40:43], v[220:223], v[196:199], v[40:43]
	v_mfma_f32_16x16x32_bf16 v[32:35], v[228:231], v[196:199], v[32:35]
	v_mfma_f32_16x16x32_bf16 v[24:27], v[220:223], v[204:207], v[24:27]
	v_mfma_f32_16x16x32_bf16 v[16:19], v[228:231], v[204:207], v[16:19]
	v_mfma_f32_16x16x32_bf16 v[8:11], v[220:223], v[212:215], v[8:11]
	v_mfma_f32_16x16x32_bf16 v[0:3], v[228:231], v[212:215], v[0:3]
	s_add_i32 s76, 0, 0x18000
	v_add_u32_e32 v150, s76, v179
	s_barrier
	s_branch .Lg359_mid
.LBB0_359:
	s_add_u32 s38, s8, 0xfffc0080
	s_addc_u32 s39, s9, -1
	s_cmp_eq_u32 s75, 12
	s_cselect_b32 s41, s21, s39
	s_cselect_b32 s40, s71, s38
	s_cselect_b32 s39, s19, s74
	s_cselect_b32 s38, s72, s73
	s_add_i32 m0, s37, 0xc000
	s_nop 0
	global_load_lds_dwordx4 v158, s[8:9]
	s_add_i32 m0, s37, 0xe000
	s_nop 0
	global_load_lds_dwordx4 v160, s[8:9]
	ds_read_b128 v[128:131], v181
	ds_read_b128 v[132:135], v181 offset:1024
	ds_read_b128 v[136:139], v181 offset:2048
	ds_read_b128 v[166:169], v181 offset:3072
	ds_read_b128 v[170:173], v182
	ds_read_b128 v[174:177], v182 offset:1024
	ds_read_b128 v[192:195], v182 offset:2048
	ds_read_b128 v[196:199], v182 offset:3072
	ds_read_b128 v[200:203], v182 offset:4096
	ds_read_b128 v[204:207], v182 offset:5120
	ds_read_b128 v[208:211], v182 offset:6144
	ds_read_b128 v[212:215], v182 offset:7168
	s_waitcnt lgkmcnt(8)
	s_barrier
	s_waitcnt lgkmcnt(0)
	s_waitcnt lgkmcnt(0)
	v_mfma_f32_16x16x32_bf16 v[124:127], v[128:131], v[170:173], v[124:127]
	v_mfma_f32_16x16x32_bf16 v[116:119], v[136:139], v[170:173], v[116:119]
	v_mfma_f32_16x16x32_bf16 v[108:111], v[128:131], v[192:195], v[108:111]
	v_mfma_f32_16x16x32_bf16 v[100:103], v[136:139], v[192:195], v[100:103]
	v_mfma_f32_16x16x32_bf16 v[92:95], v[128:131], v[200:203], v[92:95]
	v_mfma_f32_16x16x32_bf16 v[84:87], v[136:139], v[200:203], v[84:87]
	v_mfma_f32_16x16x32_bf16 v[76:79], v[128:131], v[208:211], v[76:79]
	v_mfma_f32_16x16x32_bf16 v[68:71], v[136:139], v[208:211], v[68:71]
	v_mfma_f32_16x16x32_bf16 v[124:127], v[132:135], v[174:177], v[124:127]
	v_mfma_f32_16x16x32_bf16 v[116:119], v[166:169], v[174:177], v[116:119]
	v_mfma_f32_16x16x32_bf16 v[108:111], v[132:135], v[196:199], v[108:111]
	v_mfma_f32_16x16x32_bf16 v[100:103], v[166:169], v[196:199], v[100:103]
	v_mfma_f32_16x16x32_bf16 v[92:95], v[132:135], v[204:207], v[92:95]
	v_mfma_f32_16x16x32_bf16 v[84:87], v[166:169], v[204:207], v[84:87]
	v_mfma_f32_16x16x32_bf16 v[76:79], v[132:135], v[212:215], v[76:79]
	v_mfma_f32_16x16x32_bf16 v[68:71], v[166:169], v[212:215], v[68:71]
	s_barrier
	s_add_i32 s76, s63, s46
	s_add_u32 s80, s38, 0x80
	s_addc_u32 s81, s39, 0
	s_mov_b32 m0, s76
	s_nop 0
	global_load_lds_dwordx4 v144, s[38:39]
	s_add_i32 m0, s76, 0x2000
	s_nop 0
	global_load_lds_dwordx4 v148, s[38:39]
	ds_read_b128 v[216:219], v183
	ds_read_b128 v[220:223], v183 offset:1024
	ds_read_b128 v[224:227], v183 offset:2048
	ds_read_b128 v[228:231], v183 offset:3072
	s_waitcnt vmcnt(10)
	s_barrier
	s_waitcnt lgkmcnt(0)
	s_waitcnt lgkmcnt(0)
	v_mfma_f32_16x16x32_bf16 v[120:123], v[216:219], v[170:173], v[120:123]
	v_mfma_f32_16x16x32_bf16 v[112:115], v[224:227], v[170:173], v[112:115]
	v_mfma_f32_16x16x32_bf16 v[104:107], v[216:219], v[192:195], v[104:107]
	v_mfma_f32_16x16x32_bf16 v[96:99], v[224:227], v[192:195], v[96:99]
	v_mfma_f32_16x16x32_bf16 v[88:91], v[216:219], v[200:203], v[88:91]
	v_mfma_f32_16x16x32_bf16 v[80:83], v[224:227], v[200:203], v[80:83]
	v_mfma_f32_16x16x32_bf16 v[72:75], v[216:219], v[208:211], v[72:75]
	v_mfma_f32_16x16x32_bf16 v[64:67], v[224:227], v[208:211], v[64:67]
	v_mfma_f32_16x16x32_bf16 v[120:123], v[220:223], v[174:177], v[120:123]
	v_mfma_f32_16x16x32_bf16 v[112:115], v[228:231], v[174:177], v[112:115]
	v_mfma_f32_16x16x32_bf16 v[104:107], v[220:223], v[196:199], v[104:107]
	v_mfma_f32_16x16x32_bf16 v[96:99], v[228:231], v[196:199], v[96:99]
	v_mfma_f32_16x16x32_bf16 v[88:91], v[220:223], v[204:207], v[88:91]
	v_mfma_f32_16x16x32_bf16 v[80:83], v[228:231], v[204:207], v[80:83]
	v_mfma_f32_16x16x32_bf16 v[72:75], v[220:223], v[212:215], v[72:75]
	v_mfma_f32_16x16x32_bf16 v[64:67], v[228:231], v[212:215], v[64:67]
	s_mov_b32 m0, s37
	s_add_u32 s82, s40, 0x80
	s_addc_u32 s83, s41, 0
	s_barrier
	global_load_lds_dwordx4 v142, s[40:41]
	s_mov_b32 m0, s51
	s_nop 0
	global_load_lds_dwordx4 v146, s[40:41]
	ds_read_b128 v[170:173], v182 offset:16384
	ds_read_b128 v[174:177], v182 offset:17408
	ds_read_b128 v[192:195], v182 offset:18432
	ds_read_b128 v[196:199], v182 offset:19456
	ds_read_b128 v[200:203], v182 offset:20480
	ds_read_b128 v[204:207], v182 offset:21504
	ds_read_b128 v[208:211], v182 offset:22528
	ds_read_b128 v[212:215], v182 offset:23552
	s_barrier
	s_waitcnt lgkmcnt(0)
	s_waitcnt lgkmcnt(0)
	v_mfma_f32_16x16x32_bf16 v[60:63], v[128:131], v[170:173], v[60:63]
	v_mfma_f32_16x16x32_bf16 v[52:55], v[136:139], v[170:173], v[52:55]
	v_mfma_f32_16x16x32_bf16 v[44:47], v[128:131], v[192:195], v[44:47]
	v_mfma_f32_16x16x32_bf16 v[36:39], v[136:139], v[192:195], v[36:39]
	v_mfma_f32_16x16x32_bf16 v[28:31], v[128:131], v[200:203], v[28:31]
	v_mfma_f32_16x16x32_bf16 v[20:23], v[136:139], v[200:203], v[20:23]
	v_mfma_f32_16x16x32_bf16 v[12:15], v[128:131], v[208:211], v[12:15]
	v_mfma_f32_16x16x32_bf16 v[4:7], v[136:139], v[208:211], v[4:7]
	v_mfma_f32_16x16x32_bf16 v[60:63], v[132:135], v[174:177], v[60:63]
	v_mfma_f32_16x16x32_bf16 v[52:55], v[166:169], v[174:177], v[52:55]
	v_mfma_f32_16x16x32_bf16 v[44:47], v[132:135], v[196:199], v[44:47]
	v_mfma_f32_16x16x32_bf16 v[36:39], v[166:169], v[196:199], v[36:39]
	v_mfma_f32_16x16x32_bf16 v[28:31], v[132:135], v[204:207], v[28:31]
	v_mfma_f32_16x16x32_bf16 v[20:23], v[166:169], v[204:207], v[20:23]
	v_mfma_f32_16x16x32_bf16 v[12:15], v[132:135], v[212:215], v[12:15]
	v_mfma_f32_16x16x32_bf16 v[4:7], v[166:169], v[212:215], v[4:7]
	s_barrier
	s_add_u32 s76, s38, 0x40000
	s_addc_u32 s77, s39, 0
	s_add_i32 s78, s64, s46
	s_mov_b32 m0, s78
	s_nop 0
	global_load_lds_dwordx4 v144, s[76:77]
	s_add_i32 m0, s78, 0x2000
	s_nop 0
	global_load_lds_dwordx4 v148, s[76:77]
	s_waitcnt vmcnt(8)
	s_barrier
	v_mfma_f32_16x16x32_bf16 v[56:59], v[216:219], v[170:173], v[56:59]
	v_mfma_f32_16x16x32_bf16 v[48:51], v[224:227], v[170:173], v[48:51]
	v_mfma_f32_16x16x32_bf16 v[40:43], v[216:219], v[192:195], v[40:43]
	v_mfma_f32_16x16x32_bf16 v[32:35], v[224:227], v[192:195], v[32:35]
	v_mfma_f32_16x16x32_bf16 v[24:27], v[216:219], v[200:203], v[24:27]
	v_mfma_f32_16x16x32_bf16 v[16:19], v[224:227], v[200:203], v[16:19]
	v_mfma_f32_16x16x32_bf16 v[8:11], v[216:219], v[208:211], v[8:11]
	v_mfma_f32_16x16x32_bf16 v[0:3], v[224:227], v[208:211], v[0:3]
	v_mfma_f32_16x16x32_bf16 v[56:59], v[220:223], v[174:177], v[56:59]
	v_mfma_f32_16x16x32_bf16 v[48:51], v[228:231], v[174:177], v[48:51]
	v_mfma_f32_16x16x32_bf16 v[40:43], v[220:223], v[196:199], v[40:43]
	v_mfma_f32_16x16x32_bf16 v[32:35], v[228:231], v[196:199], v[32:35]
	v_mfma_f32_16x16x32_bf16 v[24:27], v[220:223], v[204:207], v[24:27]
	v_mfma_f32_16x16x32_bf16 v[16:19], v[228:231], v[204:207], v[16:19]
	v_mfma_f32_16x16x32_bf16 v[8:11], v[220:223], v[212:215], v[8:11]
	v_mfma_f32_16x16x32_bf16 v[0:3], v[228:231], v[212:215], v[0:3]
	s_add_i32 s76, 0, 0x18000
	v_add_u32_e32 v150, s76, v179
	s_barrier
.Lg359_mid:
	s_add_u32 s40, s40, 0x40000
	s_addc_u32 s41, s41, 0
	s_mov_b32 m0, s52
	s_nop 0
	global_load_lds_dwordx4 v142, s[40:41]
	s_mov_b32 m0, s53
	s_nop 0
	global_load_lds_dwordx4 v146, s[40:41]
	ds_read_b128 v[128:131], v150
	ds_read_b128 v[132:135], v150 offset:1024
	ds_read_b128 v[136:139], v150 offset:2048
	ds_read_b128 v[166:169], v150 offset:3072
	ds_read_b128 v[170:173], v182 offset:32768
	ds_read_b128 v[174:177], v182 offset:33792
	ds_read_b128 v[192:195], v182 offset:34816
	ds_read_b128 v[196:199], v182 offset:35840
	ds_read_b128 v[200:203], v182 offset:36864
	ds_read_b128 v[204:207], v182 offset:37888
	ds_read_b128 v[208:211], v182 offset:38912
	ds_read_b128 v[212:215], v182 offset:39936
	s_waitcnt lgkmcnt(8)
	s_barrier
	s_waitcnt lgkmcnt(0)
	s_waitcnt lgkmcnt(0)
	v_mfma_f32_16x16x32_bf16 v[124:127], v[128:131], v[170:173], v[124:127]
	v_mfma_f32_16x16x32_bf16 v[116:119], v[136:139], v[170:173], v[116:119]
	v_mfma_f32_16x16x32_bf16 v[108:111], v[128:131], v[192:195], v[108:111]
	v_mfma_f32_16x16x32_bf16 v[100:103], v[136:139], v[192:195], v[100:103]
	v_mfma_f32_16x16x32_bf16 v[92:95], v[128:131], v[200:203], v[92:95]
	v_mfma_f32_16x16x32_bf16 v[84:87], v[136:139], v[200:203], v[84:87]
	v_mfma_f32_16x16x32_bf16 v[76:79], v[128:131], v[208:211], v[76:79]
	v_mfma_f32_16x16x32_bf16 v[68:71], v[136:139], v[208:211], v[68:71]
	v_mfma_f32_16x16x32_bf16 v[124:127], v[132:135], v[174:177], v[124:127]
	v_mfma_f32_16x16x32_bf16 v[116:119], v[166:169], v[174:177], v[116:119]
	v_mfma_f32_16x16x32_bf16 v[108:111], v[132:135], v[196:199], v[108:111]
	v_mfma_f32_16x16x32_bf16 v[100:103], v[166:169], v[196:199], v[100:103]
	v_mfma_f32_16x16x32_bf16 v[92:95], v[132:135], v[204:207], v[92:95]
	v_mfma_f32_16x16x32_bf16 v[84:87], v[166:169], v[204:207], v[84:87]
	v_mfma_f32_16x16x32_bf16 v[76:79], v[132:135], v[212:215], v[76:79]
	v_mfma_f32_16x16x32_bf16 v[68:71], v[166:169], v[212:215], v[68:71]
	s_barrier
	s_add_i32 s40, 0, 0x1c000
	s_add_i32 s41, s76, s46
	v_add_u32_e32 v150, s40, v179
	s_mov_b32 m0, s41
	s_nop 0
	global_load_lds_dwordx4 v144, s[80:81]
	s_add_i32 m0, s41, 0x2000
	s_nop 0
	global_load_lds_dwordx4 v148, s[80:81]
	ds_read_b128 v[216:219], v150
	ds_read_b128 v[220:223], v150 offset:1024
	ds_read_b128 v[224:227], v150 offset:2048
	ds_read_b128 v[228:231], v150 offset:3072
	s_waitcnt vmcnt(10)
	s_barrier
	s_waitcnt lgkmcnt(0)
	s_waitcnt lgkmcnt(0)
	v_mfma_f32_16x16x32_bf16 v[120:123], v[216:219], v[170:173], v[120:123]
	v_mfma_f32_16x16x32_bf16 v[112:115], v[224:227], v[170:173], v[112:115]
	v_mfma_f32_16x16x32_bf16 v[104:107], v[216:219], v[192:195], v[104:107]
	v_mfma_f32_16x16x32_bf16 v[96:99], v[224:227], v[192:195], v[96:99]
	v_mfma_f32_16x16x32_bf16 v[88:91], v[216:219], v[200:203], v[88:91]
	v_mfma_f32_16x16x32_bf16 v[80:83], v[224:227], v[200:203], v[80:83]
	v_mfma_f32_16x16x32_bf16 v[72:75], v[216:219], v[208:211], v[72:75]
	v_mfma_f32_16x16x32_bf16 v[64:67], v[224:227], v[208:211], v[64:67]
	v_mfma_f32_16x16x32_bf16 v[120:123], v[220:223], v[174:177], v[120:123]
	v_mfma_f32_16x16x32_bf16 v[112:115], v[228:231], v[174:177], v[112:115]
	v_mfma_f32_16x16x32_bf16 v[104:107], v[220:223], v[196:199], v[104:107]
	v_mfma_f32_16x16x32_bf16 v[96:99], v[228:231], v[196:199], v[96:99]
	v_mfma_f32_16x16x32_bf16 v[88:91], v[220:223], v[204:207], v[88:91]
	v_mfma_f32_16x16x32_bf16 v[80:83], v[228:231], v[204:207], v[80:83]
	v_mfma_f32_16x16x32_bf16 v[72:75], v[220:223], v[212:215], v[72:75]
	v_mfma_f32_16x16x32_bf16 v[64:67], v[228:231], v[212:215], v[64:67]
	s_mov_b32 m0, s55
	s_barrier
	global_load_lds_dwordx4 v142, s[82:83]
	s_mov_b32 m0, s56
	s_nop 0
	global_load_lds_dwordx4 v146, s[82:83]
	ds_read_b128 v[170:173], v182 offset:49152
	ds_read_b128 v[174:177], v182 offset:50176
	ds_read_b128 v[192:195], v182 offset:51200
	ds_read_b128 v[196:199], v182 offset:52224
	ds_read_b128 v[200:203], v182 offset:53248
	ds_read_b128 v[204:207], v182 offset:54272
	ds_read_b128 v[208:211], v182 offset:55296
	ds_read_b128 v[212:215], v182 offset:56320
	s_barrier
	s_waitcnt lgkmcnt(0)
	s_waitcnt lgkmcnt(0)
	v_mfma_f32_16x16x32_bf16 v[60:63], v[128:131], v[170:173], v[60:63]
	v_mfma_f32_16x16x32_bf16 v[52:55], v[136:139], v[170:173], v[52:55]
	v_mfma_f32_16x16x32_bf16 v[44:47], v[128:131], v[192:195], v[44:47]
	v_mfma_f32_16x16x32_bf16 v[36:39], v[136:139], v[192:195], v[36:39]
	v_mfma_f32_16x16x32_bf16 v[28:31], v[128:131], v[200:203], v[28:31]
	v_mfma_f32_16x16x32_bf16 v[20:23], v[136:139], v[200:203], v[20:23]
	v_mfma_f32_16x16x32_bf16 v[12:15], v[128:131], v[208:211], v[12:15]
	v_mfma_f32_16x16x32_bf16 v[4:7], v[136:139], v[208:211], v[4:7]
	v_mfma_f32_16x16x32_bf16 v[60:63], v[132:135], v[174:177], v[60:63]
	v_mfma_f32_16x16x32_bf16 v[52:55], v[166:169], v[174:177], v[52:55]
	v_mfma_f32_16x16x32_bf16 v[44:47], v[132:135], v[196:199], v[44:47]
	v_mfma_f32_16x16x32_bf16 v[36:39], v[166:169], v[196:199], v[36:39]
	v_mfma_f32_16x16x32_bf16 v[28:31], v[132:135], v[204:207], v[28:31]
	v_mfma_f32_16x16x32_bf16 v[20:23], v[166:169], v[204:207], v[20:23]
	v_mfma_f32_16x16x32_bf16 v[12:15], v[132:135], v[212:215], v[12:15]
	v_mfma_f32_16x16x32_bf16 v[4:7], v[166:169], v[212:215], v[4:7]
	s_barrier
	s_add_u32 s38, s38, 0x40080
	s_addc_u32 s39, s39, 0
	s_add_i32 s40, s40, s46
	s_mov_b32 m0, s40
	s_nop 0
	global_load_lds_dwordx4 v144, s[38:39]
	s_add_i32 m0, s40, 0x2000
	s_nop 0
	global_load_lds_dwordx4 v148, s[38:39]
	s_waitcnt vmcnt(8)
	s_barrier
	v_mfma_f32_16x16x32_bf16 v[56:59], v[216:219], v[170:173], v[56:59]
	v_mfma_f32_16x16x32_bf16 v[48:51], v[224:227], v[170:173], v[48:51]
	v_mfma_f32_16x16x32_bf16 v[40:43], v[216:219], v[192:195], v[40:43]
	v_mfma_f32_16x16x32_bf16 v[32:35], v[224:227], v[192:195], v[32:35]
	v_mfma_f32_16x16x32_bf16 v[24:27], v[216:219], v[200:203], v[24:27]
	v_mfma_f32_16x16x32_bf16 v[16:19], v[224:227], v[200:203], v[16:19]
	v_mfma_f32_16x16x32_bf16 v[8:11], v[216:219], v[208:211], v[8:11]
	v_mfma_f32_16x16x32_bf16 v[0:3], v[224:227], v[208:211], v[0:3]
	v_mfma_f32_16x16x32_bf16 v[56:59], v[220:223], v[174:177], v[56:59]
	v_mfma_f32_16x16x32_bf16 v[48:51], v[228:231], v[174:177], v[48:51]
	v_mfma_f32_16x16x32_bf16 v[40:43], v[220:223], v[196:199], v[40:43]
	v_mfma_f32_16x16x32_bf16 v[32:35], v[228:231], v[196:199], v[32:35]
	v_mfma_f32_16x16x32_bf16 v[24:27], v[220:223], v[204:207], v[24:27]
	v_mfma_f32_16x16x32_bf16 v[16:19], v[228:231], v[204:207], v[16:19]
	v_mfma_f32_16x16x32_bf16 v[8:11], v[220:223], v[212:215], v[8:11]
	v_mfma_f32_16x16x32_bf16 v[0:3], v[228:231], v[212:215], v[0:3]
	s_add_i32 s75, s75, 2
	s_add_u32 s8, s8, 0x100
	s_addc_u32 s9, s9, 0
	s_add_u32 s73, s73, 0x100
	s_addc_u32 s74, s74, 0
	s_cmp_gt_u32 s75, 13
	s_barrier
	s_cbranch_scc0 .LBB0_359
	s_setprio 0
	s_cmpk_gt_u32 s45, 0xff
	s_cbranch_scc1 .Lg359_nox
	s_barrier
	s_setprio 1

.Lg786_noy:
	s_add_u32 s30, s28, 0xfffc0080
	s_addc_u32 s31, s29, -1
	s_cmp_eq_u32 s61, 12
	s_cselect_b32 s35, s19, s31
	s_cselect_b32 s34, s57, s30
	s_cselect_b32 s31, s17, s60
	s_cselect_b32 s30, s58, s59
	s_add_i32 m0, s45, 0xc000
	s_nop 0
	global_load_lds_dwordx4 v136, s[28:29]
	s_add_i32 m0, s45, 0xe000
	s_nop 0
	global_load_lds_dwordx4 v138, s[28:29]
	ds_read_b128 v[144:147], v151
	ds_read_b128 v[156:159], v151 offset:1024
	ds_read_b128 v[160:163], v151 offset:2048
	ds_read_b128 v[164:167], v151 offset:3072
	ds_read_b128 v[168:171], v152
	ds_read_b128 v[172:175], v152 offset:1024
	ds_read_b128 v[176:179], v152 offset:2048
	ds_read_b128 v[180:183], v152 offset:3072
	ds_read_b128 v[184:187], v152 offset:4096
	ds_read_b128 v[188:191], v152 offset:5120
	ds_read_b128 v[192:195], v152 offset:6144
	ds_read_b128 v[196:199], v152 offset:7168
	s_waitcnt lgkmcnt(8)
	s_barrier
	s_waitcnt lgkmcnt(0)
	s_waitcnt lgkmcnt(0)
	v_mfma_f32_16x16x32_bf16 v[124:127], v[144:147], v[168:171], 0
	v_mfma_f32_16x16x32_bf16 v[120:123], v[160:163], v[168:171], 0
	v_mfma_f32_16x16x32_bf16 v[108:111], v[144:147], v[176:179], 0
	v_mfma_f32_16x16x32_bf16 v[104:107], v[160:163], v[176:179], 0
	v_mfma_f32_16x16x32_bf16 v[92:95], v[144:147], v[184:187], 0
	v_mfma_f32_16x16x32_bf16 v[88:91], v[160:163], v[184:187], 0
	v_mfma_f32_16x16x32_bf16 v[76:79], v[144:147], v[192:195], 0
	v_mfma_f32_16x16x32_bf16 v[72:75], v[160:163], v[192:195], 0
	v_mfma_f32_16x16x32_bf16 v[124:127], v[156:159], v[172:175], v[124:127]
	v_mfma_f32_16x16x32_bf16 v[120:123], v[164:167], v[172:175], v[120:123]
	v_mfma_f32_16x16x32_bf16 v[108:111], v[156:159], v[180:183], v[108:111]
	v_mfma_f32_16x16x32_bf16 v[104:107], v[164:167], v[180:183], v[104:107]
	v_mfma_f32_16x16x32_bf16 v[92:95], v[156:159], v[188:191], v[92:95]
	v_mfma_f32_16x16x32_bf16 v[88:91], v[164:167], v[188:191], v[88:91]
	v_mfma_f32_16x16x32_bf16 v[76:79], v[156:159], v[196:199], v[76:79]
	v_mfma_f32_16x16x32_bf16 v[72:75], v[164:167], v[196:199], v[72:75]
	s_barrier
	s_add_i32 s62, s53, s42
	s_add_u32 s80, s30, 0x80
	s_addc_u32 s81, s31, 0
	s_mov_b32 m0, s62
	s_nop 0
	global_load_lds_dwordx4 v132, s[30:31]
	s_add_i32 m0, s62, 0x2000
	s_nop 0
	global_load_lds_dwordx4 v128, s[30:31]
	ds_read_b128 v[200:203], v153
	ds_read_b128 v[204:207], v153 offset:1024
	ds_read_b128 v[208:211], v153 offset:2048
	ds_read_b128 v[212:215], v153 offset:3072
	s_waitcnt vmcnt(10)
	s_barrier
	s_waitcnt lgkmcnt(0)
	s_waitcnt lgkmcnt(0)
	v_mfma_f32_16x16x32_bf16 v[116:119], v[200:203], v[168:171], 0
	v_mfma_f32_16x16x32_bf16 v[112:115], v[208:211], v[168:171], 0
	v_mfma_f32_16x16x32_bf16 v[100:103], v[200:203], v[176:179], 0
	v_mfma_f32_16x16x32_bf16 v[96:99], v[208:211], v[176:179], 0
	v_mfma_f32_16x16x32_bf16 v[84:87], v[200:203], v[184:187], 0
	v_mfma_f32_16x16x32_bf16 v[80:83], v[208:211], v[184:187], 0
	v_mfma_f32_16x16x32_bf16 v[68:71], v[200:203], v[192:195], 0
	v_mfma_f32_16x16x32_bf16 v[64:67], v[208:211], v[192:195], 0
	v_mfma_f32_16x16x32_bf16 v[116:119], v[204:207], v[172:175], v[116:119]
	v_mfma_f32_16x16x32_bf16 v[112:115], v[212:215], v[172:175], v[112:115]
	v_mfma_f32_16x16x32_bf16 v[100:103], v[204:207], v[180:183], v[100:103]
	v_mfma_f32_16x16x32_bf16 v[96:99], v[212:215], v[180:183], v[96:99]
	v_mfma_f32_16x16x32_bf16 v[84:87], v[204:207], v[188:191], v[84:87]
	v_mfma_f32_16x16x32_bf16 v[80:83], v[212:215], v[188:191], v[80:83]
	v_mfma_f32_16x16x32_bf16 v[68:71], v[204:207], v[196:199], v[68:71]
	v_mfma_f32_16x16x32_bf16 v[64:67], v[212:215], v[196:199], v[64:67]
	s_mov_b32 m0, s45
	s_add_u32 s82, s34, 0x80
	s_addc_u32 s83, s35, 0
	s_barrier
	global_load_lds_dwordx4 v134, s[34:35]
	s_mov_b32 m0, s46
	s_nop 0
	global_load_lds_dwordx4 v130, s[34:35]
	ds_read_b128 v[168:171], v152 offset:16384
	ds_read_b128 v[172:175], v152 offset:17408
	ds_read_b128 v[176:179], v152 offset:18432
	ds_read_b128 v[180:183], v152 offset:19456
	ds_read_b128 v[184:187], v152 offset:20480
	ds_read_b128 v[188:191], v152 offset:21504
	ds_read_b128 v[192:195], v152 offset:22528
	ds_read_b128 v[196:199], v152 offset:23552
	s_barrier
	s_waitcnt lgkmcnt(0)
	s_waitcnt lgkmcnt(0)
	v_mfma_f32_16x16x32_bf16 v[60:63], v[144:147], v[168:171], 0
	v_mfma_f32_16x16x32_bf16 v[56:59], v[160:163], v[168:171], 0
	v_mfma_f32_16x16x32_bf16 v[44:47], v[144:147], v[176:179], 0
	v_mfma_f32_16x16x32_bf16 v[40:43], v[160:163], v[176:179], 0
	v_mfma_f32_16x16x32_bf16 v[28:31], v[144:147], v[184:187], 0
	v_mfma_f32_16x16x32_bf16 v[24:27], v[160:163], v[184:187], 0
	v_mfma_f32_16x16x32_bf16 v[12:15], v[144:147], v[192:195], 0
	v_mfma_f32_16x16x32_bf16 v[8:11], v[160:163], v[192:195], 0
	v_mfma_f32_16x16x32_bf16 v[60:63], v[156:159], v[172:175], v[60:63]
	v_mfma_f32_16x16x32_bf16 v[56:59], v[164:167], v[172:175], v[56:59]
	v_mfma_f32_16x16x32_bf16 v[44:47], v[156:159], v[180:183], v[44:47]
	v_mfma_f32_16x16x32_bf16 v[40:43], v[164:167], v[180:183], v[40:43]
	v_mfma_f32_16x16x32_bf16 v[28:31], v[156:159], v[188:191], v[28:31]
	v_mfma_f32_16x16x32_bf16 v[24:27], v[164:167], v[188:191], v[24:27]
	v_mfma_f32_16x16x32_bf16 v[12:15], v[156:159], v[196:199], v[12:15]
	v_mfma_f32_16x16x32_bf16 v[8:11], v[164:167], v[196:199], v[8:11]
	s_barrier
	s_add_u32 s62, s30, 0x40000
	s_addc_u32 s63, s31, 0
	s_add_i32 s64, s54, s42
	s_mov_b32 m0, s64
	s_nop 0
	global_load_lds_dwordx4 v132, s[62:63]
	s_add_i32 m0, s64, 0x2000
	s_nop 0
	global_load_lds_dwordx4 v128, s[62:63]
	s_waitcnt vmcnt(8)
	s_barrier
	v_mfma_f32_16x16x32_bf16 v[52:55], v[200:203], v[168:171], 0
	v_mfma_f32_16x16x32_bf16 v[48:51], v[208:211], v[168:171], 0
	v_mfma_f32_16x16x32_bf16 v[36:39], v[200:203], v[176:179], 0
	v_mfma_f32_16x16x32_bf16 v[32:35], v[208:211], v[176:179], 0
	v_mfma_f32_16x16x32_bf16 v[20:23], v[200:203], v[184:187], 0
	v_mfma_f32_16x16x32_bf16 v[16:19], v[208:211], v[184:187], 0
	v_mfma_f32_16x16x32_bf16 v[4:7], v[200:203], v[192:195], 0
	v_mfma_f32_16x16x32_bf16 v[0:3], v[208:211], v[192:195], 0
	v_mfma_f32_16x16x32_bf16 v[52:55], v[204:207], v[172:175], v[52:55]
	v_mfma_f32_16x16x32_bf16 v[48:51], v[212:215], v[172:175], v[48:51]
	v_mfma_f32_16x16x32_bf16 v[36:39], v[204:207], v[180:183], v[36:39]
	v_mfma_f32_16x16x32_bf16 v[32:35], v[212:215], v[180:183], v[32:35]
	v_mfma_f32_16x16x32_bf16 v[20:23], v[204:207], v[188:191], v[20:23]
	v_mfma_f32_16x16x32_bf16 v[16:19], v[212:215], v[188:191], v[16:19]
	v_mfma_f32_16x16x32_bf16 v[4:7], v[204:207], v[196:199], v[4:7]
	v_mfma_f32_16x16x32_bf16 v[0:3], v[212:215], v[196:199], v[0:3]
	s_add_i32 s62, 0, 0x18000
	v_add_u32_e32 v155, s62, v149
	s_barrier
	s_branch .Lg786_mid
.LBB0_786:
	s_add_u32 s30, s28, 0xfffc0080
	s_addc_u32 s31, s29, -1
	s_cmp_eq_u32 s61, 12
	s_cselect_b32 s35, s19, s31
	s_cselect_b32 s34, s57, s30
	s_cselect_b32 s31, s17, s60
	s_cselect_b32 s30, s58, s59
	s_add_i32 m0, s45, 0xc000
	s_nop 0
	global_load_lds_dwordx4 v136, s[28:29]
	s_add_i32 m0, s45, 0xe000
	s_nop 0
	global_load_lds_dwordx4 v138, s[28:29]
	ds_read_b128 v[144:147], v151
	ds_read_b128 v[156:159], v151 offset:1024
	ds_read_b128 v[160:163], v151 offset:2048
	ds_read_b128 v[164:167], v151 offset:3072
	ds_read_b128 v[168:171], v152
	ds_read_b128 v[172:175], v152 offset:1024
	ds_read_b128 v[176:179], v152 offset:2048
	ds_read_b128 v[180:183], v152 offset:3072
	ds_read_b128 v[184:187], v152 offset:4096
	ds_read_b128 v[188:191], v152 offset:5120
	ds_read_b128 v[192:195], v152 offset:6144
	ds_read_b128 v[196:199], v152 offset:7168
	s_waitcnt lgkmcnt(8)
	s_barrier
	s_waitcnt lgkmcnt(0)
	s_waitcnt lgkmcnt(0)
	v_mfma_f32_16x16x32_bf16 v[124:127], v[144:147], v[168:171], v[124:127]
	v_mfma_f32_16x16x32_bf16 v[120:123], v[160:163], v[168:171], v[120:123]
	v_mfma_f32_16x16x32_bf16 v[108:111], v[144:147], v[176:179], v[108:111]
	v_mfma_f32_16x16x32_bf16 v[104:107], v[160:163], v[176:179], v[104:107]
	v_mfma_f32_16x16x32_bf16 v[92:95], v[144:147], v[184:187], v[92:95]
	v_mfma_f32_16x16x32_bf16 v[88:91], v[160:163], v[184:187], v[88:91]
	v_mfma_f32_16x16x32_bf16 v[76:79], v[144:147], v[192:195], v[76:79]
	v_mfma_f32_16x16x32_bf16 v[72:75], v[160:163], v[192:195], v[72:75]
	v_mfma_f32_16x16x32_bf16 v[124:127], v[156:159], v[172:175], v[124:127]
	v_mfma_f32_16x16x32_bf16 v[120:123], v[164:167], v[172:175], v[120:123]
	v_mfma_f32_16x16x32_bf16 v[108:111], v[156:159], v[180:183], v[108:111]
	v_mfma_f32_16x16x32_bf16 v[104:107], v[164:167], v[180:183], v[104:107]
	v_mfma_f32_16x16x32_bf16 v[92:95], v[156:159], v[188:191], v[92:95]
	v_mfma_f32_16x16x32_bf16 v[88:91], v[164:167], v[188:191], v[88:91]
	v_mfma_f32_16x16x32_bf16 v[76:79], v[156:159], v[196:199], v[76:79]
	v_mfma_f32_16x16x32_bf16 v[72:75], v[164:167], v[196:199], v[72:75]
	s_barrier
	s_add_i32 s62, s53, s42
	s_add_u32 s80, s30, 0x80
	s_addc_u32 s81, s31, 0
	s_mov_b32 m0, s62
	s_nop 0
	global_load_lds_dwordx4 v132, s[30:31]
	s_add_i32 m0, s62, 0x2000
	s_nop 0
	global_load_lds_dwordx4 v128, s[30:31]
	ds_read_b128 v[200:203], v153
	ds_read_b128 v[204:207], v153 offset:1024
	ds_read_b128 v[208:211], v153 offset:2048
	ds_read_b128 v[212:215], v153 offset:3072
	s_waitcnt vmcnt(10)
	s_barrier
	s_waitcnt lgkmcnt(0)
	s_waitcnt lgkmcnt(0)
	v_mfma_f32_16x16x32_bf16 v[116:119], v[200:203], v[168:171], v[116:119]
	v_mfma_f32_16x16x32_bf16 v[112:115], v[208:211], v[168:171], v[112:115]
	v_mfma_f32_16x16x32_bf16 v[100:103], v[200:203], v[176:179], v[100:103]
	v_mfma_f32_16x16x32_bf16 v[96:99], v[208:211], v[176:179], v[96:99]
	v_mfma_f32_16x16x32_bf16 v[84:87], v[200:203], v[184:187], v[84:87]
	v_mfma_f32_16x16x32_bf16 v[80:83], v[208:211], v[184:187], v[80:83]
	v_mfma_f32_16x16x32_bf16 v[68:71], v[200:203], v[192:195], v[68:71]
	v_mfma_f32_16x16x32_bf16 v[64:67], v[208:211], v[192:195], v[64:67]
	v_mfma_f32_16x16x32_bf16 v[116:119], v[204:207], v[172:175], v[116:119]
	v_mfma_f32_16x16x32_bf16 v[112:115], v[212:215], v[172:175], v[112:115]
	v_mfma_f32_16x16x32_bf16 v[100:103], v[204:207], v[180:183], v[100:103]
	v_mfma_f32_16x16x32_bf16 v[96:99], v[212:215], v[180:183], v[96:99]
	v_mfma_f32_16x16x32_bf16 v[84:87], v[204:207], v[188:191], v[84:87]
	v_mfma_f32_16x16x32_bf16 v[80:83], v[212:215], v[188:191], v[80:83]
	v_mfma_f32_16x16x32_bf16 v[68:71], v[204:207], v[196:199], v[68:71]
	v_mfma_f32_16x16x32_bf16 v[64:67], v[212:215], v[196:199], v[64:67]
	s_mov_b32 m0, s45
	s_add_u32 s82, s34, 0x80
	s_addc_u32 s83, s35, 0
	s_barrier
	global_load_lds_dwordx4 v134, s[34:35]
	s_mov_b32 m0, s46
	s_nop 0
	global_load_lds_dwordx4 v130, s[34:35]
	ds_read_b128 v[168:171], v152 offset:16384
	ds_read_b128 v[172:175], v152 offset:17408
	ds_read_b128 v[176:179], v152 offset:18432
	ds_read_b128 v[180:183], v152 offset:19456
	ds_read_b128 v[184:187], v152 offset:20480
	ds_read_b128 v[188:191], v152 offset:21504
	ds_read_b128 v[192:195], v152 offset:22528
	ds_read_b128 v[196:199], v152 offset:23552
	s_barrier
	s_waitcnt lgkmcnt(0)
	s_waitcnt lgkmcnt(0)
	v_mfma_f32_16x16x32_bf16 v[60:63], v[144:147], v[168:171], v[60:63]
	v_mfma_f32_16x16x32_bf16 v[56:59], v[160:163], v[168:171], v[56:59]
	v_mfma_f32_16x16x32_bf16 v[44:47], v[144:147], v[176:179], v[44:47]
	v_mfma_f32_16x16x32_bf16 v[40:43], v[160:163], v[176:179], v[40:43]
	v_mfma_f32_16x16x32_bf16 v[28:31], v[144:147], v[184:187], v[28:31]
	v_mfma_f32_16x16x32_bf16 v[24:27], v[160:163], v[184:187], v[24:27]
	v_mfma_f32_16x16x32_bf16 v[12:15], v[144:147], v[192:195], v[12:15]
	v_mfma_f32_16x16x32_bf16 v[8:11], v[160:163], v[192:195], v[8:11]
	v_mfma_f32_16x16x32_bf16 v[60:63], v[156:159], v[172:175], v[60:63]
	v_mfma_f32_16x16x32_bf16 v[56:59], v[164:167], v[172:175], v[56:59]
	v_mfma_f32_16x16x32_bf16 v[44:47], v[156:159], v[180:183], v[44:47]
	v_mfma_f32_16x16x32_bf16 v[40:43], v[164:167], v[180:183], v[40:43]
	v_mfma_f32_16x16x32_bf16 v[28:31], v[156:159], v[188:191], v[28:31]
	v_mfma_f32_16x16x32_bf16 v[24:27], v[164:167], v[188:191], v[24:27]
	v_mfma_f32_16x16x32_bf16 v[12:15], v[156:159], v[196:199], v[12:15]
	v_mfma_f32_16x16x32_bf16 v[8:11], v[164:167], v[196:199], v[8:11]
	s_barrier
	s_add_u32 s62, s30, 0x40000
	s_addc_u32 s63, s31, 0
	s_add_i32 s64, s54, s42
	s_mov_b32 m0, s64
	s_nop 0
	global_load_lds_dwordx4 v132, s[62:63]
	s_add_i32 m0, s64, 0x2000
	s_nop 0
	global_load_lds_dwordx4 v128, s[62:63]
	s_waitcnt vmcnt(8)
	s_barrier
	v_mfma_f32_16x16x32_bf16 v[52:55], v[200:203], v[168:171], v[52:55]
	v_mfma_f32_16x16x32_bf16 v[48:51], v[208:211], v[168:171], v[48:51]
	v_mfma_f32_16x16x32_bf16 v[36:39], v[200:203], v[176:179], v[36:39]
	v_mfma_f32_16x16x32_bf16 v[32:35], v[208:211], v[176:179], v[32:35]
	v_mfma_f32_16x16x32_bf16 v[20:23], v[200:203], v[184:187], v[20:23]
	v_mfma_f32_16x16x32_bf16 v[16:19], v[208:211], v[184:187], v[16:19]
	v_mfma_f32_16x16x32_bf16 v[4:7], v[200:203], v[192:195], v[4:7]
	v_mfma_f32_16x16x32_bf16 v[0:3], v[208:211], v[192:195], v[0:3]
	v_mfma_f32_16x16x32_bf16 v[52:55], v[204:207], v[172:175], v[52:55]
	v_mfma_f32_16x16x32_bf16 v[48:51], v[212:215], v[172:175], v[48:51]
	v_mfma_f32_16x16x32_bf16 v[36:39], v[204:207], v[180:183], v[36:39]
	v_mfma_f32_16x16x32_bf16 v[32:35], v[212:215], v[180:183], v[32:35]
	v_mfma_f32_16x16x32_bf16 v[20:23], v[204:207], v[188:191], v[20:23]
	v_mfma_f32_16x16x32_bf16 v[16:19], v[212:215], v[188:191], v[16:19]
	v_mfma_f32_16x16x32_bf16 v[4:7], v[204:207], v[196:199], v[4:7]
	v_mfma_f32_16x16x32_bf16 v[0:3], v[212:215], v[196:199], v[0:3]
	s_add_i32 s62, 0, 0x18000
	v_add_u32_e32 v155, s62, v149
	s_barrier
.Lg786_mid:
	s_add_u32 s34, s34, 0x40000
	s_addc_u32 s35, s35, 0
	s_mov_b32 m0, s47
	s_nop 0
	global_load_lds_dwordx4 v134, s[34:35]
	s_mov_b32 m0, s48
	s_nop 0
	global_load_lds_dwordx4 v130, s[34:35]
	ds_read_b128 v[144:147], v155
	ds_read_b128 v[156:159], v155 offset:1024
	ds_read_b128 v[160:163], v155 offset:2048
	ds_read_b128 v[164:167], v155 offset:3072
	ds_read_b128 v[168:171], v152 offset:32768
	ds_read_b128 v[172:175], v152 offset:33792
	ds_read_b128 v[176:179], v152 offset:34816
	ds_read_b128 v[180:183], v152 offset:35840
	ds_read_b128 v[184:187], v152 offset:36864
	ds_read_b128 v[188:191], v152 offset:37888
	ds_read_b128 v[192:195], v152 offset:38912
	ds_read_b128 v[196:199], v152 offset:39936
	s_waitcnt lgkmcnt(8)
	s_barrier
	s_waitcnt lgkmcnt(0)
	s_waitcnt lgkmcnt(0)
	v_mfma_f32_16x16x32_bf16 v[124:127], v[144:147], v[168:171], v[124:127]
	v_mfma_f32_16x16x32_bf16 v[120:123], v[160:163], v[168:171], v[120:123]
	v_mfma_f32_16x16x32_bf16 v[108:111], v[144:147], v[176:179], v[108:111]
	v_mfma_f32_16x16x32_bf16 v[104:107], v[160:163], v[176:179], v[104:107]
	v_mfma_f32_16x16x32_bf16 v[92:95], v[144:147], v[184:187], v[92:95]
	v_mfma_f32_16x16x32_bf16 v[88:91], v[160:163], v[184:187], v[88:91]
	v_mfma_f32_16x16x32_bf16 v[76:79], v[144:147], v[192:195], v[76:79]
	v_mfma_f32_16x16x32_bf16 v[72:75], v[160:163], v[192:195], v[72:75]
	v_mfma_f32_16x16x32_bf16 v[124:127], v[156:159], v[172:175], v[124:127]
	v_mfma_f32_16x16x32_bf16 v[120:123], v[164:167], v[172:175], v[120:123]
	v_mfma_f32_16x16x32_bf16 v[108:111], v[156:159], v[180:183], v[108:111]
	v_mfma_f32_16x16x32_bf16 v[104:107], v[164:167], v[180:183], v[104:107]
	v_mfma_f32_16x16x32_bf16 v[92:95], v[156:159], v[188:191], v[92:95]
	v_mfma_f32_16x16x32_bf16 v[88:91], v[164:167], v[188:191], v[88:91]
	v_mfma_f32_16x16x32_bf16 v[76:79], v[156:159], v[196:199], v[76:79]
	v_mfma_f32_16x16x32_bf16 v[72:75], v[164:167], v[196:199], v[72:75]
	s_barrier
	s_add_i32 s34, 0, 0x1c000
	s_add_i32 s35, s62, s42
	v_add_u32_e32 v155, s34, v149
	s_mov_b32 m0, s35
	s_nop 0
	global_load_lds_dwordx4 v132, s[80:81]
	s_add_i32 m0, s35, 0x2000
	s_nop 0
	global_load_lds_dwordx4 v128, s[80:81]
	ds_read_b128 v[200:203], v155
	ds_read_b128 v[204:207], v155 offset:1024
	ds_read_b128 v[208:211], v155 offset:2048
	ds_read_b128 v[212:215], v155 offset:3072
	s_waitcnt vmcnt(10)
	s_barrier
	s_waitcnt lgkmcnt(0)
	s_waitcnt lgkmcnt(0)
	v_mfma_f32_16x16x32_bf16 v[116:119], v[200:203], v[168:171], v[116:119]
	v_mfma_f32_16x16x32_bf16 v[112:115], v[208:211], v[168:171], v[112:115]
	v_mfma_f32_16x16x32_bf16 v[100:103], v[200:203], v[176:179], v[100:103]
	v_mfma_f32_16x16x32_bf16 v[96:99], v[208:211], v[176:179], v[96:99]
	v_mfma_f32_16x16x32_bf16 v[84:87], v[200:203], v[184:187], v[84:87]
	v_mfma_f32_16x16x32_bf16 v[80:83], v[208:211], v[184:187], v[80:83]
	v_mfma_f32_16x16x32_bf16 v[68:71], v[200:203], v[192:195], v[68:71]
	v_mfma_f32_16x16x32_bf16 v[64:67], v[208:211], v[192:195], v[64:67]
	v_mfma_f32_16x16x32_bf16 v[116:119], v[204:207], v[172:175], v[116:119]
	v_mfma_f32_16x16x32_bf16 v[112:115], v[212:215], v[172:175], v[112:115]
	v_mfma_f32_16x16x32_bf16 v[100:103], v[204:207], v[180:183], v[100:103]
	v_mfma_f32_16x16x32_bf16 v[96:99], v[212:215], v[180:183], v[96:99]
	v_mfma_f32_16x16x32_bf16 v[84:87], v[204:207], v[188:191], v[84:87]
	v_mfma_f32_16x16x32_bf16 v[80:83], v[212:215], v[188:191], v[80:83]
	v_mfma_f32_16x16x32_bf16 v[68:71], v[204:207], v[196:199], v[68:71]
	v_mfma_f32_16x16x32_bf16 v[64:67], v[212:215], v[196:199], v[64:67]
	s_mov_b32 m0, s50
	s_barrier
	global_load_lds_dwordx4 v134, s[82:83]
	s_mov_b32 m0, s51
	s_nop 0
	global_load_lds_dwordx4 v130, s[82:83]
	ds_read_b128 v[168:171], v152 offset:49152
	ds_read_b128 v[172:175], v152 offset:50176
	ds_read_b128 v[176:179], v152 offset:51200
	ds_read_b128 v[180:183], v152 offset:52224
	ds_read_b128 v[184:187], v152 offset:53248
	ds_read_b128 v[188:191], v152 offset:54272
	ds_read_b128 v[192:195], v152 offset:55296
	ds_read_b128 v[196:199], v152 offset:56320
	s_barrier
	s_waitcnt lgkmcnt(0)
	s_waitcnt lgkmcnt(0)
	v_mfma_f32_16x16x32_bf16 v[60:63], v[144:147], v[168:171], v[60:63]
	v_mfma_f32_16x16x32_bf16 v[56:59], v[160:163], v[168:171], v[56:59]
	v_mfma_f32_16x16x32_bf16 v[44:47], v[144:147], v[176:179], v[44:47]
	v_mfma_f32_16x16x32_bf16 v[40:43], v[160:163], v[176:179], v[40:43]
	v_mfma_f32_16x16x32_bf16 v[28:31], v[144:147], v[184:187], v[28:31]
	v_mfma_f32_16x16x32_bf16 v[24:27], v[160:163], v[184:187], v[24:27]
	v_mfma_f32_16x16x32_bf16 v[12:15], v[144:147], v[192:195], v[12:15]
	v_mfma_f32_16x16x32_bf16 v[8:11], v[160:163], v[192:195], v[8:11]
	v_mfma_f32_16x16x32_bf16 v[60:63], v[156:159], v[172:175], v[60:63]
	v_mfma_f32_16x16x32_bf16 v[56:59], v[164:167], v[172:175], v[56:59]
	v_mfma_f32_16x16x32_bf16 v[44:47], v[156:159], v[180:183], v[44:47]
	v_mfma_f32_16x16x32_bf16 v[40:43], v[164:167], v[180:183], v[40:43]
	v_mfma_f32_16x16x32_bf16 v[28:31], v[156:159], v[188:191], v[28:31]
	v_mfma_f32_16x16x32_bf16 v[24:27], v[164:167], v[188:191], v[24:27]
	v_mfma_f32_16x16x32_bf16 v[12:15], v[156:159], v[196:199], v[12:15]
	v_mfma_f32_16x16x32_bf16 v[8:11], v[164:167], v[196:199], v[8:11]
	s_barrier
	s_add_u32 s30, s30, 0x40080
	s_addc_u32 s31, s31, 0
	s_add_i32 s34, s34, s42
	s_mov_b32 m0, s34
	s_nop 0
	global_load_lds_dwordx4 v132, s[30:31]
	s_add_i32 m0, s34, 0x2000
	s_nop 0
	global_load_lds_dwordx4 v128, s[30:31]
	s_waitcnt vmcnt(8)
	s_barrier
	v_mfma_f32_16x16x32_bf16 v[52:55], v[200:203], v[168:171], v[52:55]
	v_mfma_f32_16x16x32_bf16 v[48:51], v[208:211], v[168:171], v[48:51]
	v_mfma_f32_16x16x32_bf16 v[36:39], v[200:203], v[176:179], v[36:39]
	v_mfma_f32_16x16x32_bf16 v[32:35], v[208:211], v[176:179], v[32:35]
	v_mfma_f32_16x16x32_bf16 v[20:23], v[200:203], v[184:187], v[20:23]
	v_mfma_f32_16x16x32_bf16 v[16:19], v[208:211], v[184:187], v[16:19]
	v_mfma_f32_16x16x32_bf16 v[4:7], v[200:203], v[192:195], v[4:7]
	v_mfma_f32_16x16x32_bf16 v[0:3], v[208:211], v[192:195], v[0:3]
	v_mfma_f32_16x16x32_bf16 v[52:55], v[204:207], v[172:175], v[52:55]
	v_mfma_f32_16x16x32_bf16 v[48:51], v[212:215], v[172:175], v[48:51]
	v_mfma_f32_16x16x32_bf16 v[36:39], v[204:207], v[180:183], v[36:39]
	v_mfma_f32_16x16x32_bf16 v[32:35], v[212:215], v[180:183], v[32:35]
	v_mfma_f32_16x16x32_bf16 v[20:23], v[204:207], v[188:191], v[20:23]
	v_mfma_f32_16x16x32_bf16 v[16:19], v[212:215], v[188:191], v[16:19]
	v_mfma_f32_16x16x32_bf16 v[4:7], v[204:207], v[196:199], v[4:7]
	v_mfma_f32_16x16x32_bf16 v[0:3], v[212:215], v[196:199], v[0:3]
	s_add_i32 s61, s61, 2
	s_add_u32 s28, s28, 0x100
	s_addc_u32 s29, s29, 0
	s_add_u32 s59, s59, 0x100
	s_addc_u32 s60, s60, 0
	s_cmp_gt_u32 s61, 13
	s_barrier
	s_cbranch_scc0 .LBB0_786
	s_setprio 0
	v_lshl_add_u32 v146, s8, 8, v148
	v_ashrrev_i32_e32 v147, 31, v146
	v_lshl_or_b32 v144, s56, 8, v150
	v_lshlrev_b64 v[156:157], 11, v[146:147]
	v_ashrrev_i32_e32 v145, 31, v144
	v_lshl_add_u64 v[156:157], s[10:11], 0, v[156:157]
	v_lshl_add_u64 v[166:167], v[144:145], 1, v[156:157]
	global_load_dwordx4 v[158:161], v[166:167], off
	global_load_dwordx4 v[162:165], v[166:167], off offset:256
	s_mov_b64 s[84:85], 0x8000
	s_mov_b64 s[86:87], 0x28000
	v_lshl_add_u64 v[232:233], v[166:167], 0, s[84:85]
	global_load_dwordx4 v[176:179], v[232:233], off
	global_load_dwordx4 v[180:183], v[232:233], off offset:256
	v_lshl_add_u64 v[232:233], v[232:233], 0, s[84:85]
	global_load_dwordx4 v[184:187], v[232:233], off
	global_load_dwordx4 v[188:191], v[232:233], off offset:256
	v_lshl_add_u64 v[232:233], v[232:233], 0, s[84:85]
	global_load_dwordx4 v[192:195], v[232:233], off
	global_load_dwordx4 v[196:199], v[232:233], off offset:256
	v_lshl_add_u64 v[232:233], v[232:233], 0, s[86:87]
	global_load_dwordx4 v[200:203], v[232:233], off
	global_load_dwordx4 v[204:207], v[232:233], off offset:256
	v_lshl_add_u64 v[232:233], v[232:233], 0, s[84:85]
	global_load_dwordx4 v[208:211], v[232:233], off
	global_load_dwordx4 v[212:215], v[232:233], off offset:256
	v_lshl_add_u64 v[232:233], v[232:233], 0, s[84:85]
	global_load_dwordx4 v[216:219], v[232:233], off
	global_load_dwordx4 v[220:223], v[232:233], off offset:256
	v_lshl_add_u64 v[232:233], v[232:233], 0, s[84:85]
	global_load_dwordx4 v[224:227], v[232:233], off
	global_load_dwordx4 v[228:231], v[232:233], off offset:256
	s_cmpk_gt_u32 s37, 0xff
	s_cbranch_scc1 .Lg786_nox
	s_barrier
	s_setprio 1

.Lg893_noy:
	s_add_u32 s26, s20, 0xfffc0080
	s_addc_u32 s27, s21, -1
	s_cmp_eq_u32 s57, 12
	s_cselect_b32 s29, s13, s27
	s_cselect_b32 s28, s53, s26
	s_cselect_b32 s27, s11, s56
	s_cselect_b32 s26, s54, s55
	s_add_i32 m0, s19, 0xc000
	s_nop 0
	global_load_lds_dwordx4 v136, s[20:21]
	s_add_i32 m0, s19, 0xe000
	s_nop 0
	global_load_lds_dwordx4 v138, s[20:21]
	ds_read_b128 v[152:155], v148
	ds_read_b128 v[156:159], v148 offset:1024
	ds_read_b128 v[160:163], v148 offset:2048
	ds_read_b128 v[164:167], v148 offset:3072
	ds_read_b128 v[168:171], v149
	ds_read_b128 v[172:175], v149 offset:1024
	ds_read_b128 v[176:179], v149 offset:2048
	ds_read_b128 v[180:183], v149 offset:3072
	ds_read_b128 v[184:187], v149 offset:4096
	ds_read_b128 v[188:191], v149 offset:5120
	ds_read_b128 v[192:195], v149 offset:6144
	ds_read_b128 v[196:199], v149 offset:7168
	s_waitcnt lgkmcnt(8)
	s_barrier
	s_waitcnt lgkmcnt(0)
	s_waitcnt lgkmcnt(0)
	v_mfma_f32_16x16x32_bf16 v[124:127], v[152:155], v[168:171], 0
	v_mfma_f32_16x16x32_bf16 v[120:123], v[160:163], v[168:171], 0
	v_mfma_f32_16x16x32_bf16 v[108:111], v[152:155], v[176:179], 0
	v_mfma_f32_16x16x32_bf16 v[104:107], v[160:163], v[176:179], 0
	v_mfma_f32_16x16x32_bf16 v[92:95], v[152:155], v[184:187], 0
	v_mfma_f32_16x16x32_bf16 v[88:91], v[160:163], v[184:187], 0
	v_mfma_f32_16x16x32_bf16 v[76:79], v[152:155], v[192:195], 0
	v_mfma_f32_16x16x32_bf16 v[72:75], v[160:163], v[192:195], 0
	v_mfma_f32_16x16x32_bf16 v[124:127], v[156:159], v[172:175], v[124:127]
	v_mfma_f32_16x16x32_bf16 v[120:123], v[164:167], v[172:175], v[120:123]
	v_mfma_f32_16x16x32_bf16 v[108:111], v[156:159], v[180:183], v[108:111]
	v_mfma_f32_16x16x32_bf16 v[104:107], v[164:167], v[180:183], v[104:107]
	v_mfma_f32_16x16x32_bf16 v[92:95], v[156:159], v[188:191], v[92:95]
	v_mfma_f32_16x16x32_bf16 v[88:91], v[164:167], v[188:191], v[88:91]
	v_mfma_f32_16x16x32_bf16 v[76:79], v[156:159], v[196:199], v[76:79]
	v_mfma_f32_16x16x32_bf16 v[72:75], v[164:167], v[196:199], v[72:75]
	s_barrier
	s_add_i32 s58, s47, s31
	s_add_u32 s80, s26, 0x80
	s_addc_u32 s81, s27, 0
	s_mov_b32 m0, s58
	s_nop 0
	global_load_lds_dwordx4 v132, s[26:27]
	s_add_i32 m0, s58, 0x2000
	s_nop 0
	global_load_lds_dwordx4 v128, s[26:27]
	ds_read_b128 v[200:203], v150
	ds_read_b128 v[204:207], v150 offset:1024
	ds_read_b128 v[208:211], v150 offset:2048
	ds_read_b128 v[212:215], v150 offset:3072
	s_waitcnt vmcnt(10)
	s_barrier
	s_waitcnt lgkmcnt(0)
	s_waitcnt lgkmcnt(0)
	v_mfma_f32_16x16x32_bf16 v[116:119], v[200:203], v[168:171], 0
	v_mfma_f32_16x16x32_bf16 v[112:115], v[208:211], v[168:171], 0
	v_mfma_f32_16x16x32_bf16 v[100:103], v[200:203], v[176:179], 0
	v_mfma_f32_16x16x32_bf16 v[96:99], v[208:211], v[176:179], 0
	v_mfma_f32_16x16x32_bf16 v[84:87], v[200:203], v[184:187], 0
	v_mfma_f32_16x16x32_bf16 v[80:83], v[208:211], v[184:187], 0
	v_mfma_f32_16x16x32_bf16 v[68:71], v[200:203], v[192:195], 0
	v_mfma_f32_16x16x32_bf16 v[64:67], v[208:211], v[192:195], 0
	v_mfma_f32_16x16x32_bf16 v[116:119], v[204:207], v[172:175], v[116:119]
	v_mfma_f32_16x16x32_bf16 v[112:115], v[212:215], v[172:175], v[112:115]
	v_mfma_f32_16x16x32_bf16 v[100:103], v[204:207], v[180:183], v[100:103]
	v_mfma_f32_16x16x32_bf16 v[96:99], v[212:215], v[180:183], v[96:99]
	v_mfma_f32_16x16x32_bf16 v[84:87], v[204:207], v[188:191], v[84:87]
	v_mfma_f32_16x16x32_bf16 v[80:83], v[212:215], v[188:191], v[80:83]
	v_mfma_f32_16x16x32_bf16 v[68:71], v[204:207], v[196:199], v[68:71]
	v_mfma_f32_16x16x32_bf16 v[64:67], v[212:215], v[196:199], v[64:67]
	s_mov_b32 m0, s19
	s_add_u32 s82, s28, 0x80
	s_addc_u32 s83, s29, 0
	s_barrier
	global_load_lds_dwordx4 v134, s[28:29]
	s_mov_b32 m0, s42
	s_nop 0
	global_load_lds_dwordx4 v130, s[28:29]
	ds_read_b128 v[168:171], v149 offset:16384
	ds_read_b128 v[172:175], v149 offset:17408
	ds_read_b128 v[176:179], v149 offset:18432
	ds_read_b128 v[180:183], v149 offset:19456
	ds_read_b128 v[184:187], v149 offset:20480
	ds_read_b128 v[188:191], v149 offset:21504
	ds_read_b128 v[192:195], v149 offset:22528
	ds_read_b128 v[196:199], v149 offset:23552
	s_barrier
	s_waitcnt lgkmcnt(0)
	s_waitcnt lgkmcnt(0)
	v_mfma_f32_16x16x32_bf16 v[60:63], v[152:155], v[168:171], 0
	v_mfma_f32_16x16x32_bf16 v[56:59], v[160:163], v[168:171], 0
	v_mfma_f32_16x16x32_bf16 v[44:47], v[152:155], v[176:179], 0
	v_mfma_f32_16x16x32_bf16 v[40:43], v[160:163], v[176:179], 0
	v_mfma_f32_16x16x32_bf16 v[28:31], v[152:155], v[184:187], 0
	v_mfma_f32_16x16x32_bf16 v[24:27], v[160:163], v[184:187], 0
	v_mfma_f32_16x16x32_bf16 v[12:15], v[152:155], v[192:195], 0
	v_mfma_f32_16x16x32_bf16 v[8:11], v[160:163], v[192:195], 0
	v_mfma_f32_16x16x32_bf16 v[60:63], v[156:159], v[172:175], v[60:63]
	v_mfma_f32_16x16x32_bf16 v[56:59], v[164:167], v[172:175], v[56:59]
	v_mfma_f32_16x16x32_bf16 v[44:47], v[156:159], v[180:183], v[44:47]
	v_mfma_f32_16x16x32_bf16 v[40:43], v[164:167], v[180:183], v[40:43]
	v_mfma_f32_16x16x32_bf16 v[28:31], v[156:159], v[188:191], v[28:31]
	v_mfma_f32_16x16x32_bf16 v[24:27], v[164:167], v[188:191], v[24:27]
	v_mfma_f32_16x16x32_bf16 v[12:15], v[156:159], v[196:199], v[12:15]
	v_mfma_f32_16x16x32_bf16 v[8:11], v[164:167], v[196:199], v[8:11]
	s_barrier
	s_add_u32 s58, s26, 0x40000
	s_addc_u32 s59, s27, 0
	s_add_i32 s60, s48, s31
	s_mov_b32 m0, s60
	s_nop 0
	global_load_lds_dwordx4 v132, s[58:59]
	s_add_i32 m0, s60, 0x2000
	s_nop 0
	global_load_lds_dwordx4 v128, s[58:59]
	s_waitcnt vmcnt(8)
	s_barrier
	v_mfma_f32_16x16x32_bf16 v[52:55], v[200:203], v[168:171], 0
	v_mfma_f32_16x16x32_bf16 v[48:51], v[208:211], v[168:171], 0
	v_mfma_f32_16x16x32_bf16 v[36:39], v[200:203], v[176:179], 0
	v_mfma_f32_16x16x32_bf16 v[32:35], v[208:211], v[176:179], 0
	v_mfma_f32_16x16x32_bf16 v[20:23], v[200:203], v[184:187], 0
	v_mfma_f32_16x16x32_bf16 v[16:19], v[208:211], v[184:187], 0
	v_mfma_f32_16x16x32_bf16 v[4:7], v[200:203], v[192:195], 0
	v_mfma_f32_16x16x32_bf16 v[0:3], v[208:211], v[192:195], 0
	v_mfma_f32_16x16x32_bf16 v[52:55], v[204:207], v[172:175], v[52:55]
	v_mfma_f32_16x16x32_bf16 v[48:51], v[212:215], v[172:175], v[48:51]
	v_mfma_f32_16x16x32_bf16 v[36:39], v[204:207], v[180:183], v[36:39]
	v_mfma_f32_16x16x32_bf16 v[32:35], v[212:215], v[180:183], v[32:35]
	v_mfma_f32_16x16x32_bf16 v[20:23], v[204:207], v[188:191], v[20:23]
	v_mfma_f32_16x16x32_bf16 v[16:19], v[212:215], v[188:191], v[16:19]
	v_mfma_f32_16x16x32_bf16 v[4:7], v[204:207], v[196:199], v[4:7]
	v_mfma_f32_16x16x32_bf16 v[0:3], v[212:215], v[196:199], v[0:3]
	s_add_i32 s58, 0, 0x18000
	v_add_u32_e32 v151, s58, v145
	s_barrier
	s_branch .Lg893_mid
.LBB0_893:
	s_add_u32 s26, s20, 0xfffc0080
	s_addc_u32 s27, s21, -1
	s_cmp_eq_u32 s57, 12
	s_cselect_b32 s29, s13, s27
	s_cselect_b32 s28, s53, s26
	s_cselect_b32 s27, s11, s56
	s_cselect_b32 s26, s54, s55
	s_add_i32 m0, s19, 0xc000
	s_nop 0
	global_load_lds_dwordx4 v136, s[20:21]
	s_add_i32 m0, s19, 0xe000
	s_nop 0
	global_load_lds_dwordx4 v138, s[20:21]
	ds_read_b128 v[152:155], v148
	ds_read_b128 v[156:159], v148 offset:1024
	ds_read_b128 v[160:163], v148 offset:2048
	ds_read_b128 v[164:167], v148 offset:3072
	ds_read_b128 v[168:171], v149
	ds_read_b128 v[172:175], v149 offset:1024
	ds_read_b128 v[176:179], v149 offset:2048
	ds_read_b128 v[180:183], v149 offset:3072
	ds_read_b128 v[184:187], v149 offset:4096
	ds_read_b128 v[188:191], v149 offset:5120
	ds_read_b128 v[192:195], v149 offset:6144
	ds_read_b128 v[196:199], v149 offset:7168
	s_waitcnt lgkmcnt(8)
	s_barrier
	s_waitcnt lgkmcnt(0)
	s_waitcnt lgkmcnt(0)
	v_mfma_f32_16x16x32_bf16 v[124:127], v[152:155], v[168:171], v[124:127]
	v_mfma_f32_16x16x32_bf16 v[120:123], v[160:163], v[168:171], v[120:123]
	v_mfma_f32_16x16x32_bf16 v[108:111], v[152:155], v[176:179], v[108:111]
	v_mfma_f32_16x16x32_bf16 v[104:107], v[160:163], v[176:179], v[104:107]
	v_mfma_f32_16x16x32_bf16 v[92:95], v[152:155], v[184:187], v[92:95]
	v_mfma_f32_16x16x32_bf16 v[88:91], v[160:163], v[184:187], v[88:91]
	v_mfma_f32_16x16x32_bf16 v[76:79], v[152:155], v[192:195], v[76:79]
	v_mfma_f32_16x16x32_bf16 v[72:75], v[160:163], v[192:195], v[72:75]
	v_mfma_f32_16x16x32_bf16 v[124:127], v[156:159], v[172:175], v[124:127]
	v_mfma_f32_16x16x32_bf16 v[120:123], v[164:167], v[172:175], v[120:123]
	v_mfma_f32_16x16x32_bf16 v[108:111], v[156:159], v[180:183], v[108:111]
	v_mfma_f32_16x16x32_bf16 v[104:107], v[164:167], v[180:183], v[104:107]
	v_mfma_f32_16x16x32_bf16 v[92:95], v[156:159], v[188:191], v[92:95]
	v_mfma_f32_16x16x32_bf16 v[88:91], v[164:167], v[188:191], v[88:91]
	v_mfma_f32_16x16x32_bf16 v[76:79], v[156:159], v[196:199], v[76:79]
	v_mfma_f32_16x16x32_bf16 v[72:75], v[164:167], v[196:199], v[72:75]
	s_barrier
	s_add_i32 s58, s47, s31
	s_add_u32 s80, s26, 0x80
	s_addc_u32 s81, s27, 0
	s_mov_b32 m0, s58
	s_nop 0
	global_load_lds_dwordx4 v132, s[26:27]
	s_add_i32 m0, s58, 0x2000
	s_nop 0
	global_load_lds_dwordx4 v128, s[26:27]
	ds_read_b128 v[200:203], v150
	ds_read_b128 v[204:207], v150 offset:1024
	ds_read_b128 v[208:211], v150 offset:2048
	ds_read_b128 v[212:215], v150 offset:3072
	s_waitcnt vmcnt(10)
	s_barrier
	s_waitcnt lgkmcnt(0)
	s_waitcnt lgkmcnt(0)
	v_mfma_f32_16x16x32_bf16 v[116:119], v[200:203], v[168:171], v[116:119]
	v_mfma_f32_16x16x32_bf16 v[112:115], v[208:211], v[168:171], v[112:115]
	v_mfma_f32_16x16x32_bf16 v[100:103], v[200:203], v[176:179], v[100:103]
	v_mfma_f32_16x16x32_bf16 v[96:99], v[208:211], v[176:179], v[96:99]
	v_mfma_f32_16x16x32_bf16 v[84:87], v[200:203], v[184:187], v[84:87]
	v_mfma_f32_16x16x32_bf16 v[80:83], v[208:211], v[184:187], v[80:83]
	v_mfma_f32_16x16x32_bf16 v[68:71], v[200:203], v[192:195], v[68:71]
	v_mfma_f32_16x16x32_bf16 v[64:67], v[208:211], v[192:195], v[64:67]
	v_mfma_f32_16x16x32_bf16 v[116:119], v[204:207], v[172:175], v[116:119]
	v_mfma_f32_16x16x32_bf16 v[112:115], v[212:215], v[172:175], v[112:115]
	v_mfma_f32_16x16x32_bf16 v[100:103], v[204:207], v[180:183], v[100:103]
	v_mfma_f32_16x16x32_bf16 v[96:99], v[212:215], v[180:183], v[96:99]
	v_mfma_f32_16x16x32_bf16 v[84:87], v[204:207], v[188:191], v[84:87]
	v_mfma_f32_16x16x32_bf16 v[80:83], v[212:215], v[188:191], v[80:83]
	v_mfma_f32_16x16x32_bf16 v[68:71], v[204:207], v[196:199], v[68:71]
	v_mfma_f32_16x16x32_bf16 v[64:67], v[212:215], v[196:199], v[64:67]
	s_mov_b32 m0, s19
	s_add_u32 s82, s28, 0x80
	s_addc_u32 s83, s29, 0
	s_barrier
	global_load_lds_dwordx4 v134, s[28:29]
	s_mov_b32 m0, s42
	s_nop 0
	global_load_lds_dwordx4 v130, s[28:29]
	ds_read_b128 v[168:171], v149 offset:16384
	ds_read_b128 v[172:175], v149 offset:17408
	ds_read_b128 v[176:179], v149 offset:18432
	ds_read_b128 v[180:183], v149 offset:19456
	ds_read_b128 v[184:187], v149 offset:20480
	ds_read_b128 v[188:191], v149 offset:21504
	ds_read_b128 v[192:195], v149 offset:22528
	ds_read_b128 v[196:199], v149 offset:23552
	s_barrier
	s_waitcnt lgkmcnt(0)
	s_waitcnt lgkmcnt(0)
	v_mfma_f32_16x16x32_bf16 v[60:63], v[152:155], v[168:171], v[60:63]
	v_mfma_f32_16x16x32_bf16 v[56:59], v[160:163], v[168:171], v[56:59]
	v_mfma_f32_16x16x32_bf16 v[44:47], v[152:155], v[176:179], v[44:47]
	v_mfma_f32_16x16x32_bf16 v[40:43], v[160:163], v[176:179], v[40:43]
	v_mfma_f32_16x16x32_bf16 v[28:31], v[152:155], v[184:187], v[28:31]
	v_mfma_f32_16x16x32_bf16 v[24:27], v[160:163], v[184:187], v[24:27]
	v_mfma_f32_16x16x32_bf16 v[12:15], v[152:155], v[192:195], v[12:15]
	v_mfma_f32_16x16x32_bf16 v[8:11], v[160:163], v[192:195], v[8:11]
	v_mfma_f32_16x16x32_bf16 v[60:63], v[156:159], v[172:175], v[60:63]
	v_mfma_f32_16x16x32_bf16 v[56:59], v[164:167], v[172:175], v[56:59]
	v_mfma_f32_16x16x32_bf16 v[44:47], v[156:159], v[180:183], v[44:47]
	v_mfma_f32_16x16x32_bf16 v[40:43], v[164:167], v[180:183], v[40:43]
	v_mfma_f32_16x16x32_bf16 v[28:31], v[156:159], v[188:191], v[28:31]
	v_mfma_f32_16x16x32_bf16 v[24:27], v[164:167], v[188:191], v[24:27]
	v_mfma_f32_16x16x32_bf16 v[12:15], v[156:159], v[196:199], v[12:15]
	v_mfma_f32_16x16x32_bf16 v[8:11], v[164:167], v[196:199], v[8:11]
	s_barrier
	s_add_u32 s58, s26, 0x40000
	s_addc_u32 s59, s27, 0
	s_add_i32 s60, s48, s31
	s_mov_b32 m0, s60
	s_nop 0
	global_load_lds_dwordx4 v132, s[58:59]
	s_add_i32 m0, s60, 0x2000
	s_nop 0
	global_load_lds_dwordx4 v128, s[58:59]
	s_waitcnt vmcnt(8)
	s_barrier
	v_mfma_f32_16x16x32_bf16 v[52:55], v[200:203], v[168:171], v[52:55]
	v_mfma_f32_16x16x32_bf16 v[48:51], v[208:211], v[168:171], v[48:51]
	v_mfma_f32_16x16x32_bf16 v[36:39], v[200:203], v[176:179], v[36:39]
	v_mfma_f32_16x16x32_bf16 v[32:35], v[208:211], v[176:179], v[32:35]
	v_mfma_f32_16x16x32_bf16 v[20:23], v[200:203], v[184:187], v[20:23]
	v_mfma_f32_16x16x32_bf16 v[16:19], v[208:211], v[184:187], v[16:19]
	v_mfma_f32_16x16x32_bf16 v[4:7], v[200:203], v[192:195], v[4:7]
	v_mfma_f32_16x16x32_bf16 v[0:3], v[208:211], v[192:195], v[0:3]
	v_mfma_f32_16x16x32_bf16 v[52:55], v[204:207], v[172:175], v[52:55]
	v_mfma_f32_16x16x32_bf16 v[48:51], v[212:215], v[172:175], v[48:51]
	v_mfma_f32_16x16x32_bf16 v[36:39], v[204:207], v[180:183], v[36:39]
	v_mfma_f32_16x16x32_bf16 v[32:35], v[212:215], v[180:183], v[32:35]
	v_mfma_f32_16x16x32_bf16 v[20:23], v[204:207], v[188:191], v[20:23]
	v_mfma_f32_16x16x32_bf16 v[16:19], v[212:215], v[188:191], v[16:19]
	v_mfma_f32_16x16x32_bf16 v[4:7], v[204:207], v[196:199], v[4:7]
	v_mfma_f32_16x16x32_bf16 v[0:3], v[212:215], v[196:199], v[0:3]
	s_add_i32 s58, 0, 0x18000
	v_add_u32_e32 v151, s58, v145
	s_barrier
.Lg893_mid:
	s_add_u32 s28, s28, 0x40000
	s_addc_u32 s29, s29, 0
	s_mov_b32 m0, s43
	s_nop 0
	global_load_lds_dwordx4 v134, s[28:29]
	s_mov_b32 m0, s44
	s_nop 0
	global_load_lds_dwordx4 v130, s[28:29]
	ds_read_b128 v[152:155], v151
	ds_read_b128 v[156:159], v151 offset:1024
	ds_read_b128 v[160:163], v151 offset:2048
	ds_read_b128 v[164:167], v151 offset:3072
	ds_read_b128 v[168:171], v149 offset:32768
	ds_read_b128 v[172:175], v149 offset:33792
	ds_read_b128 v[176:179], v149 offset:34816
	ds_read_b128 v[180:183], v149 offset:35840
	ds_read_b128 v[184:187], v149 offset:36864
	ds_read_b128 v[188:191], v149 offset:37888
	ds_read_b128 v[192:195], v149 offset:38912
	ds_read_b128 v[196:199], v149 offset:39936
	s_waitcnt lgkmcnt(8)
	s_barrier
	s_waitcnt lgkmcnt(0)
	s_waitcnt lgkmcnt(0)
	v_mfma_f32_16x16x32_bf16 v[124:127], v[152:155], v[168:171], v[124:127]
	v_mfma_f32_16x16x32_bf16 v[120:123], v[160:163], v[168:171], v[120:123]
	v_mfma_f32_16x16x32_bf16 v[108:111], v[152:155], v[176:179], v[108:111]
	v_mfma_f32_16x16x32_bf16 v[104:107], v[160:163], v[176:179], v[104:107]
	v_mfma_f32_16x16x32_bf16 v[92:95], v[152:155], v[184:187], v[92:95]
	v_mfma_f32_16x16x32_bf16 v[88:91], v[160:163], v[184:187], v[88:91]
	v_mfma_f32_16x16x32_bf16 v[76:79], v[152:155], v[192:195], v[76:79]
	v_mfma_f32_16x16x32_bf16 v[72:75], v[160:163], v[192:195], v[72:75]
	v_mfma_f32_16x16x32_bf16 v[124:127], v[156:159], v[172:175], v[124:127]
	v_mfma_f32_16x16x32_bf16 v[120:123], v[164:167], v[172:175], v[120:123]
	v_mfma_f32_16x16x32_bf16 v[108:111], v[156:159], v[180:183], v[108:111]
	v_mfma_f32_16x16x32_bf16 v[104:107], v[164:167], v[180:183], v[104:107]
	v_mfma_f32_16x16x32_bf16 v[92:95], v[156:159], v[188:191], v[92:95]
	v_mfma_f32_16x16x32_bf16 v[88:91], v[164:167], v[188:191], v[88:91]
	v_mfma_f32_16x16x32_bf16 v[76:79], v[156:159], v[196:199], v[76:79]
	v_mfma_f32_16x16x32_bf16 v[72:75], v[164:167], v[196:199], v[72:75]
	s_barrier
	s_add_i32 s28, 0, 0x1c000
	s_add_i32 s29, s58, s31
	v_add_u32_e32 v151, s28, v145
	s_mov_b32 m0, s29
	s_nop 0
	global_load_lds_dwordx4 v132, s[80:81]
	s_add_i32 m0, s29, 0x2000
	s_nop 0
	global_load_lds_dwordx4 v128, s[80:81]
	ds_read_b128 v[200:203], v151
	ds_read_b128 v[204:207], v151 offset:1024
	ds_read_b128 v[208:211], v151 offset:2048
	ds_read_b128 v[212:215], v151 offset:3072
	s_waitcnt vmcnt(10)
	s_barrier
	s_waitcnt lgkmcnt(0)
	s_waitcnt lgkmcnt(0)
	v_mfma_f32_16x16x32_bf16 v[116:119], v[200:203], v[168:171], v[116:119]
	v_mfma_f32_16x16x32_bf16 v[112:115], v[208:211], v[168:171], v[112:115]
	v_mfma_f32_16x16x32_bf16 v[100:103], v[200:203], v[176:179], v[100:103]
	v_mfma_f32_16x16x32_bf16 v[96:99], v[208:211], v[176:179], v[96:99]
	v_mfma_f32_16x16x32_bf16 v[84:87], v[200:203], v[184:187], v[84:87]
	v_mfma_f32_16x16x32_bf16 v[80:83], v[208:211], v[184:187], v[80:83]
	v_mfma_f32_16x16x32_bf16 v[68:71], v[200:203], v[192:195], v[68:71]
	v_mfma_f32_16x16x32_bf16 v[64:67], v[208:211], v[192:195], v[64:67]
	v_mfma_f32_16x16x32_bf16 v[116:119], v[204:207], v[172:175], v[116:119]
	v_mfma_f32_16x16x32_bf16 v[112:115], v[212:215], v[172:175], v[112:115]
	v_mfma_f32_16x16x32_bf16 v[100:103], v[204:207], v[180:183], v[100:103]
	v_mfma_f32_16x16x32_bf16 v[96:99], v[212:215], v[180:183], v[96:99]
	v_mfma_f32_16x16x32_bf16 v[84:87], v[204:207], v[188:191], v[84:87]
	v_mfma_f32_16x16x32_bf16 v[80:83], v[212:215], v[188:191], v[80:83]
	v_mfma_f32_16x16x32_bf16 v[68:71], v[204:207], v[196:199], v[68:71]
	v_mfma_f32_16x16x32_bf16 v[64:67], v[212:215], v[196:199], v[64:67]
	s_mov_b32 m0, s45
	s_barrier
	global_load_lds_dwordx4 v134, s[82:83]
	s_mov_b32 m0, s46
	s_nop 0
	global_load_lds_dwordx4 v130, s[82:83]
	ds_read_b128 v[168:171], v149 offset:49152
	ds_read_b128 v[172:175], v149 offset:50176
	ds_read_b128 v[176:179], v149 offset:51200
	ds_read_b128 v[180:183], v149 offset:52224
	ds_read_b128 v[184:187], v149 offset:53248
	ds_read_b128 v[188:191], v149 offset:54272
	ds_read_b128 v[192:195], v149 offset:55296
	ds_read_b128 v[196:199], v149 offset:56320
	s_barrier
	s_waitcnt lgkmcnt(0)
	s_waitcnt lgkmcnt(0)
	v_mfma_f32_16x16x32_bf16 v[60:63], v[152:155], v[168:171], v[60:63]
	v_mfma_f32_16x16x32_bf16 v[56:59], v[160:163], v[168:171], v[56:59]
	v_mfma_f32_16x16x32_bf16 v[44:47], v[152:155], v[176:179], v[44:47]
	v_mfma_f32_16x16x32_bf16 v[40:43], v[160:163], v[176:179], v[40:43]
	v_mfma_f32_16x16x32_bf16 v[28:31], v[152:155], v[184:187], v[28:31]
	v_mfma_f32_16x16x32_bf16 v[24:27], v[160:163], v[184:187], v[24:27]
	v_mfma_f32_16x16x32_bf16 v[12:15], v[152:155], v[192:195], v[12:15]
	v_mfma_f32_16x16x32_bf16 v[8:11], v[160:163], v[192:195], v[8:11]
	v_mfma_f32_16x16x32_bf16 v[60:63], v[156:159], v[172:175], v[60:63]
	v_mfma_f32_16x16x32_bf16 v[56:59], v[164:167], v[172:175], v[56:59]
	v_mfma_f32_16x16x32_bf16 v[44:47], v[156:159], v[180:183], v[44:47]
	v_mfma_f32_16x16x32_bf16 v[40:43], v[164:167], v[180:183], v[40:43]
	v_mfma_f32_16x16x32_bf16 v[28:31], v[156:159], v[188:191], v[28:31]
	v_mfma_f32_16x16x32_bf16 v[24:27], v[164:167], v[188:191], v[24:27]
	v_mfma_f32_16x16x32_bf16 v[12:15], v[156:159], v[196:199], v[12:15]
	v_mfma_f32_16x16x32_bf16 v[8:11], v[164:167], v[196:199], v[8:11]
	s_barrier
	s_add_u32 s26, s26, 0x40080
	s_addc_u32 s27, s27, 0
	s_add_i32 s28, s28, s31
	s_mov_b32 m0, s28
	s_nop 0
	global_load_lds_dwordx4 v132, s[26:27]
	s_add_i32 m0, s28, 0x2000
	s_nop 0
	global_load_lds_dwordx4 v128, s[26:27]
	s_waitcnt vmcnt(8)
	s_barrier
	v_mfma_f32_16x16x32_bf16 v[52:55], v[200:203], v[168:171], v[52:55]
	v_mfma_f32_16x16x32_bf16 v[48:51], v[208:211], v[168:171], v[48:51]
	v_mfma_f32_16x16x32_bf16 v[36:39], v[200:203], v[176:179], v[36:39]
	v_mfma_f32_16x16x32_bf16 v[32:35], v[208:211], v[176:179], v[32:35]
	v_mfma_f32_16x16x32_bf16 v[20:23], v[200:203], v[184:187], v[20:23]
	v_mfma_f32_16x16x32_bf16 v[16:19], v[208:211], v[184:187], v[16:19]
	v_mfma_f32_16x16x32_bf16 v[4:7], v[200:203], v[192:195], v[4:7]
	v_mfma_f32_16x16x32_bf16 v[0:3], v[208:211], v[192:195], v[0:3]
	v_mfma_f32_16x16x32_bf16 v[52:55], v[204:207], v[172:175], v[52:55]
	v_mfma_f32_16x16x32_bf16 v[48:51], v[212:215], v[172:175], v[48:51]
	v_mfma_f32_16x16x32_bf16 v[36:39], v[204:207], v[180:183], v[36:39]
	v_mfma_f32_16x16x32_bf16 v[32:35], v[212:215], v[180:183], v[32:35]
	v_mfma_f32_16x16x32_bf16 v[20:23], v[204:207], v[188:191], v[20:23]
	v_mfma_f32_16x16x32_bf16 v[16:19], v[212:215], v[188:191], v[16:19]
	v_mfma_f32_16x16x32_bf16 v[4:7], v[204:207], v[196:199], v[4:7]
	v_mfma_f32_16x16x32_bf16 v[0:3], v[212:215], v[196:199], v[0:3]
	s_add_i32 s57, s57, 2
	s_add_u32 s20, s20, 0x100
	s_addc_u32 s21, s21, 0
	s_add_u32 s55, s55, 0x100
	s_addc_u32 s56, s56, 0
	s_cmp_gt_u32 s57, 13
	s_barrier
	s_cbranch_scc0 .LBB0_893
	s_setprio 0
	s_cmpk_gt_u32 s30, 0xff
	s_cbranch_scc1 .Lg893_nox
	s_barrier
	s_setprio 1

.Lg973_noy:
	s_add_u32 s22, s20, 0x100
	s_addc_u32 s23, s21, 0
	s_cmp_eq_u32 s56, 40
	s_cselect_b32 s27, s5, s23
	s_cselect_b32 s26, s4, s22
	s_cselect_b32 s25, s7, s55
	s_cselect_b32 s24, s6, s54
	s_add_i32 m0, s37, 0xc000
	s_nop 0
	global_load_lds_dwordx4 v138, s[20:21]
	s_add_i32 m0, s37, 0xe000
	s_nop 0
	global_load_lds_dwordx4 v140, s[20:21]
	ds_read_b128 v[146:149], v203
	ds_read_b128 v[150:153], v203 offset:1024
	ds_read_b128 v[154:157], v203 offset:2048
	ds_read_b128 v[158:161], v203 offset:3072
	ds_read_b128 v[162:165], v204
	ds_read_b128 v[166:169], v204 offset:1024
	ds_read_b128 v[170:173], v204 offset:2048
	ds_read_b128 v[174:177], v204 offset:3072
	ds_read_b128 v[178:181], v204 offset:4096
	ds_read_b128 v[182:185], v204 offset:5120
	ds_read_b128 v[186:189], v204 offset:6144
	ds_read_b128 v[190:193], v204 offset:7168
	s_waitcnt lgkmcnt(8)
	s_barrier
	s_waitcnt lgkmcnt(0)
	s_waitcnt lgkmcnt(0)
	v_mfma_f32_16x16x32_bf16 v[124:127], v[146:149], v[162:165], 0
	v_mfma_f32_16x16x32_bf16 v[120:123], v[154:157], v[162:165], 0
	v_mfma_f32_16x16x32_bf16 v[108:111], v[146:149], v[170:173], 0
	v_mfma_f32_16x16x32_bf16 v[104:107], v[154:157], v[170:173], 0
	v_mfma_f32_16x16x32_bf16 v[92:95], v[146:149], v[178:181], 0
	v_mfma_f32_16x16x32_bf16 v[88:91], v[154:157], v[178:181], 0
	v_mfma_f32_16x16x32_bf16 v[76:79], v[146:149], v[186:189], 0
	v_mfma_f32_16x16x32_bf16 v[72:75], v[154:157], v[186:189], 0
	v_mfma_f32_16x16x32_bf16 v[124:127], v[150:153], v[166:169], v[124:127]
	v_mfma_f32_16x16x32_bf16 v[120:123], v[158:161], v[166:169], v[120:123]
	v_mfma_f32_16x16x32_bf16 v[108:111], v[150:153], v[174:177], v[108:111]
	v_mfma_f32_16x16x32_bf16 v[104:107], v[158:161], v[174:177], v[104:107]
	v_mfma_f32_16x16x32_bf16 v[92:95], v[150:153], v[182:185], v[92:95]
	v_mfma_f32_16x16x32_bf16 v[88:91], v[158:161], v[182:185], v[88:91]
	v_mfma_f32_16x16x32_bf16 v[76:79], v[150:153], v[190:193], v[76:79]
	v_mfma_f32_16x16x32_bf16 v[72:75], v[158:161], v[190:193], v[72:75]
	s_barrier
	s_add_i32 s20, s47, s36
	s_add_u32 s80, s24, 0x80
	s_addc_u32 s81, s25, 0
	s_mov_b32 m0, s20
	s_nop 0
	global_load_lds_dwordx4 v130, s[24:25]
	s_add_i32 m0, s20, 0x2000
	s_nop 0
	global_load_lds_dwordx4 v134, s[24:25]
	ds_read_b128 v[194:197], v205
	ds_read_b128 v[208:211], v205 offset:1024
	ds_read_b128 v[212:215], v205 offset:2048
	ds_read_b128 v[216:219], v205 offset:3072
	s_waitcnt vmcnt(10)
	s_barrier
	s_waitcnt lgkmcnt(0)
	s_waitcnt lgkmcnt(0)
	v_mfma_f32_16x16x32_bf16 v[116:119], v[194:197], v[162:165], 0
	v_mfma_f32_16x16x32_bf16 v[112:115], v[212:215], v[162:165], 0
	v_mfma_f32_16x16x32_bf16 v[100:103], v[194:197], v[170:173], 0
	v_mfma_f32_16x16x32_bf16 v[96:99], v[212:215], v[170:173], 0
	v_mfma_f32_16x16x32_bf16 v[84:87], v[194:197], v[178:181], 0
	v_mfma_f32_16x16x32_bf16 v[80:83], v[212:215], v[178:181], 0
	v_mfma_f32_16x16x32_bf16 v[68:71], v[194:197], v[186:189], 0
	v_mfma_f32_16x16x32_bf16 v[64:67], v[212:215], v[186:189], 0
	v_mfma_f32_16x16x32_bf16 v[116:119], v[208:211], v[166:169], v[116:119]
	v_mfma_f32_16x16x32_bf16 v[112:115], v[216:219], v[166:169], v[112:115]
	v_mfma_f32_16x16x32_bf16 v[100:103], v[208:211], v[174:177], v[100:103]
	v_mfma_f32_16x16x32_bf16 v[96:99], v[216:219], v[174:177], v[96:99]
	v_mfma_f32_16x16x32_bf16 v[84:87], v[208:211], v[182:185], v[84:87]
	v_mfma_f32_16x16x32_bf16 v[80:83], v[216:219], v[182:185], v[80:83]
	v_mfma_f32_16x16x32_bf16 v[68:71], v[208:211], v[190:193], v[68:71]
	v_mfma_f32_16x16x32_bf16 v[64:67], v[216:219], v[190:193], v[64:67]
	s_mov_b32 m0, s37
	s_add_u32 s82, s26, 0x80
	s_addc_u32 s83, s27, 0
	s_barrier
	global_load_lds_dwordx4 v128, s[26:27]
	s_mov_b32 m0, s38
	s_nop 0
	global_load_lds_dwordx4 v132, s[26:27]
	ds_read_b128 v[162:165], v204 offset:16384
	ds_read_b128 v[166:169], v204 offset:17408
	ds_read_b128 v[170:173], v204 offset:18432
	ds_read_b128 v[174:177], v204 offset:19456
	ds_read_b128 v[178:181], v204 offset:20480
	ds_read_b128 v[182:185], v204 offset:21504
	ds_read_b128 v[186:189], v204 offset:22528
	ds_read_b128 v[190:193], v204 offset:23552
	s_barrier
	s_waitcnt lgkmcnt(0)
	s_waitcnt lgkmcnt(0)
	v_mfma_f32_16x16x32_bf16 v[60:63], v[146:149], v[162:165], 0
	v_mfma_f32_16x16x32_bf16 v[56:59], v[154:157], v[162:165], 0
	v_mfma_f32_16x16x32_bf16 v[44:47], v[146:149], v[170:173], 0
	v_mfma_f32_16x16x32_bf16 v[40:43], v[154:157], v[170:173], 0
	v_mfma_f32_16x16x32_bf16 v[28:31], v[146:149], v[178:181], 0
	v_mfma_f32_16x16x32_bf16 v[24:27], v[154:157], v[178:181], 0
	v_mfma_f32_16x16x32_bf16 v[12:15], v[146:149], v[186:189], 0
	v_mfma_f32_16x16x32_bf16 v[8:11], v[154:157], v[186:189], 0
	v_mfma_f32_16x16x32_bf16 v[60:63], v[150:153], v[166:169], v[60:63]
	v_mfma_f32_16x16x32_bf16 v[56:59], v[158:161], v[166:169], v[56:59]
	v_mfma_f32_16x16x32_bf16 v[44:47], v[150:153], v[174:177], v[44:47]
	v_mfma_f32_16x16x32_bf16 v[40:43], v[158:161], v[174:177], v[40:43]
	v_mfma_f32_16x16x32_bf16 v[28:31], v[150:153], v[182:185], v[28:31]
	v_mfma_f32_16x16x32_bf16 v[24:27], v[158:161], v[182:185], v[24:27]
	v_mfma_f32_16x16x32_bf16 v[12:15], v[150:153], v[190:193], v[12:15]
	v_mfma_f32_16x16x32_bf16 v[8:11], v[158:161], v[190:193], v[8:11]
	s_barrier
	s_add_u32 s20, s24, 0xb0000
	s_addc_u32 s21, s25, 0
	s_add_i32 s57, s48, s36
	s_mov_b32 m0, s57
	s_nop 0
	global_load_lds_dwordx4 v130, s[20:21]
	s_add_i32 m0, s57, 0x2000
	s_nop 0
	global_load_lds_dwordx4 v134, s[20:21]
	s_waitcnt vmcnt(8)
	s_barrier
	v_mfma_f32_16x16x32_bf16 v[52:55], v[194:197], v[162:165], 0
	v_mfma_f32_16x16x32_bf16 v[48:51], v[212:215], v[162:165], 0
	v_mfma_f32_16x16x32_bf16 v[36:39], v[194:197], v[170:173], 0
	v_mfma_f32_16x16x32_bf16 v[32:35], v[212:215], v[170:173], 0
	v_mfma_f32_16x16x32_bf16 v[20:23], v[194:197], v[178:181], 0
	v_mfma_f32_16x16x32_bf16 v[16:19], v[212:215], v[178:181], 0
	v_mfma_f32_16x16x32_bf16 v[4:7], v[194:197], v[186:189], 0
	v_mfma_f32_16x16x32_bf16 v[0:3], v[212:215], v[186:189], 0
	v_mfma_f32_16x16x32_bf16 v[52:55], v[208:211], v[166:169], v[52:55]
	v_mfma_f32_16x16x32_bf16 v[48:51], v[216:219], v[166:169], v[48:51]
	v_mfma_f32_16x16x32_bf16 v[36:39], v[208:211], v[174:177], v[36:39]
	v_mfma_f32_16x16x32_bf16 v[32:35], v[216:219], v[174:177], v[32:35]
	v_mfma_f32_16x16x32_bf16 v[20:23], v[208:211], v[182:185], v[20:23]
	v_mfma_f32_16x16x32_bf16 v[16:19], v[216:219], v[182:185], v[16:19]
	v_mfma_f32_16x16x32_bf16 v[4:7], v[208:211], v[190:193], v[4:7]
	v_mfma_f32_16x16x32_bf16 v[0:3], v[216:219], v[190:193], v[0:3]
	s_add_i32 s57, 0, 0x18000
	v_add_u32_e32 v158, s57, v201
	s_barrier
	s_branch .Lg973_mid
.LBB0_973:
	s_add_u32 s22, s20, 0x100
	s_addc_u32 s23, s21, 0
	s_cmp_eq_u32 s56, 40
	s_cselect_b32 s27, s5, s23
	s_cselect_b32 s26, s4, s22
	s_cselect_b32 s25, s7, s55
	s_cselect_b32 s24, s6, s54
	s_add_i32 m0, s37, 0xc000
	s_nop 0
	global_load_lds_dwordx4 v138, s[20:21]
	s_add_i32 m0, s37, 0xe000
	s_nop 0
	global_load_lds_dwordx4 v140, s[20:21]
	ds_read_b128 v[146:149], v203
	ds_read_b128 v[150:153], v203 offset:1024
	ds_read_b128 v[154:157], v203 offset:2048
	ds_read_b128 v[158:161], v203 offset:3072
	ds_read_b128 v[162:165], v204
	ds_read_b128 v[166:169], v204 offset:1024
	ds_read_b128 v[170:173], v204 offset:2048
	ds_read_b128 v[174:177], v204 offset:3072
	ds_read_b128 v[178:181], v204 offset:4096
	ds_read_b128 v[182:185], v204 offset:5120
	ds_read_b128 v[186:189], v204 offset:6144
	ds_read_b128 v[190:193], v204 offset:7168
	s_waitcnt lgkmcnt(8)
	s_barrier
	s_waitcnt lgkmcnt(0)
	s_waitcnt lgkmcnt(0)
	v_mfma_f32_16x16x32_bf16 v[124:127], v[146:149], v[162:165], v[124:127]
	v_mfma_f32_16x16x32_bf16 v[120:123], v[154:157], v[162:165], v[120:123]
	v_mfma_f32_16x16x32_bf16 v[108:111], v[146:149], v[170:173], v[108:111]
	v_mfma_f32_16x16x32_bf16 v[104:107], v[154:157], v[170:173], v[104:107]
	v_mfma_f32_16x16x32_bf16 v[92:95], v[146:149], v[178:181], v[92:95]
	v_mfma_f32_16x16x32_bf16 v[88:91], v[154:157], v[178:181], v[88:91]
	v_mfma_f32_16x16x32_bf16 v[76:79], v[146:149], v[186:189], v[76:79]
	v_mfma_f32_16x16x32_bf16 v[72:75], v[154:157], v[186:189], v[72:75]
	v_mfma_f32_16x16x32_bf16 v[124:127], v[150:153], v[166:169], v[124:127]
	v_mfma_f32_16x16x32_bf16 v[120:123], v[158:161], v[166:169], v[120:123]
	v_mfma_f32_16x16x32_bf16 v[108:111], v[150:153], v[174:177], v[108:111]
	v_mfma_f32_16x16x32_bf16 v[104:107], v[158:161], v[174:177], v[104:107]
	v_mfma_f32_16x16x32_bf16 v[92:95], v[150:153], v[182:185], v[92:95]
	v_mfma_f32_16x16x32_bf16 v[88:91], v[158:161], v[182:185], v[88:91]
	v_mfma_f32_16x16x32_bf16 v[76:79], v[150:153], v[190:193], v[76:79]
	v_mfma_f32_16x16x32_bf16 v[72:75], v[158:161], v[190:193], v[72:75]
	s_barrier
	s_add_i32 s20, s47, s36
	s_add_u32 s80, s24, 0x80
	s_addc_u32 s81, s25, 0
	s_mov_b32 m0, s20
	s_nop 0
	global_load_lds_dwordx4 v130, s[24:25]
	s_add_i32 m0, s20, 0x2000
	s_nop 0
	global_load_lds_dwordx4 v134, s[24:25]
	ds_read_b128 v[194:197], v205
	ds_read_b128 v[208:211], v205 offset:1024
	ds_read_b128 v[212:215], v205 offset:2048
	ds_read_b128 v[216:219], v205 offset:3072
	s_waitcnt vmcnt(10)
	s_barrier
	s_waitcnt lgkmcnt(0)
	s_waitcnt lgkmcnt(0)
	v_mfma_f32_16x16x32_bf16 v[116:119], v[194:197], v[162:165], v[116:119]
	v_mfma_f32_16x16x32_bf16 v[112:115], v[212:215], v[162:165], v[112:115]
	v_mfma_f32_16x16x32_bf16 v[100:103], v[194:197], v[170:173], v[100:103]
	v_mfma_f32_16x16x32_bf16 v[96:99], v[212:215], v[170:173], v[96:99]
	v_mfma_f32_16x16x32_bf16 v[84:87], v[194:197], v[178:181], v[84:87]
	v_mfma_f32_16x16x32_bf16 v[80:83], v[212:215], v[178:181], v[80:83]
	v_mfma_f32_16x16x32_bf16 v[68:71], v[194:197], v[186:189], v[68:71]
	v_mfma_f32_16x16x32_bf16 v[64:67], v[212:215], v[186:189], v[64:67]
	v_mfma_f32_16x16x32_bf16 v[116:119], v[208:211], v[166:169], v[116:119]
	v_mfma_f32_16x16x32_bf16 v[112:115], v[216:219], v[166:169], v[112:115]
	v_mfma_f32_16x16x32_bf16 v[100:103], v[208:211], v[174:177], v[100:103]
	v_mfma_f32_16x16x32_bf16 v[96:99], v[216:219], v[174:177], v[96:99]
	v_mfma_f32_16x16x32_bf16 v[84:87], v[208:211], v[182:185], v[84:87]
	v_mfma_f32_16x16x32_bf16 v[80:83], v[216:219], v[182:185], v[80:83]
	v_mfma_f32_16x16x32_bf16 v[68:71], v[208:211], v[190:193], v[68:71]
	v_mfma_f32_16x16x32_bf16 v[64:67], v[216:219], v[190:193], v[64:67]
	s_mov_b32 m0, s37
	s_add_u32 s82, s26, 0x80
	s_addc_u32 s83, s27, 0
	s_barrier
	global_load_lds_dwordx4 v128, s[26:27]
	s_mov_b32 m0, s38
	s_nop 0
	global_load_lds_dwordx4 v132, s[26:27]
	ds_read_b128 v[162:165], v204 offset:16384
	ds_read_b128 v[166:169], v204 offset:17408
	ds_read_b128 v[170:173], v204 offset:18432
	ds_read_b128 v[174:177], v204 offset:19456
	ds_read_b128 v[178:181], v204 offset:20480
	ds_read_b128 v[182:185], v204 offset:21504
	ds_read_b128 v[186:189], v204 offset:22528
	ds_read_b128 v[190:193], v204 offset:23552
	s_barrier
	s_waitcnt lgkmcnt(0)
	s_waitcnt lgkmcnt(0)
	v_mfma_f32_16x16x32_bf16 v[60:63], v[146:149], v[162:165], v[60:63]
	v_mfma_f32_16x16x32_bf16 v[56:59], v[154:157], v[162:165], v[56:59]
	v_mfma_f32_16x16x32_bf16 v[44:47], v[146:149], v[170:173], v[44:47]
	v_mfma_f32_16x16x32_bf16 v[40:43], v[154:157], v[170:173], v[40:43]
	v_mfma_f32_16x16x32_bf16 v[28:31], v[146:149], v[178:181], v[28:31]
	v_mfma_f32_16x16x32_bf16 v[24:27], v[154:157], v[178:181], v[24:27]
	v_mfma_f32_16x16x32_bf16 v[12:15], v[146:149], v[186:189], v[12:15]
	v_mfma_f32_16x16x32_bf16 v[8:11], v[154:157], v[186:189], v[8:11]
	v_mfma_f32_16x16x32_bf16 v[60:63], v[150:153], v[166:169], v[60:63]
	v_mfma_f32_16x16x32_bf16 v[56:59], v[158:161], v[166:169], v[56:59]
	v_mfma_f32_16x16x32_bf16 v[44:47], v[150:153], v[174:177], v[44:47]
	v_mfma_f32_16x16x32_bf16 v[40:43], v[158:161], v[174:177], v[40:43]
	v_mfma_f32_16x16x32_bf16 v[28:31], v[150:153], v[182:185], v[28:31]
	v_mfma_f32_16x16x32_bf16 v[24:27], v[158:161], v[182:185], v[24:27]
	v_mfma_f32_16x16x32_bf16 v[12:15], v[150:153], v[190:193], v[12:15]
	v_mfma_f32_16x16x32_bf16 v[8:11], v[158:161], v[190:193], v[8:11]
	s_barrier
	s_add_u32 s20, s24, 0xb0000
	s_addc_u32 s21, s25, 0
	s_add_i32 s57, s48, s36
	s_mov_b32 m0, s57
	s_nop 0
	global_load_lds_dwordx4 v130, s[20:21]
	s_add_i32 m0, s57, 0x2000
	s_nop 0
	global_load_lds_dwordx4 v134, s[20:21]
	s_waitcnt vmcnt(8)
	s_barrier
	v_mfma_f32_16x16x32_bf16 v[52:55], v[194:197], v[162:165], v[52:55]
	v_mfma_f32_16x16x32_bf16 v[48:51], v[212:215], v[162:165], v[48:51]
	v_mfma_f32_16x16x32_bf16 v[36:39], v[194:197], v[170:173], v[36:39]
	v_mfma_f32_16x16x32_bf16 v[32:35], v[212:215], v[170:173], v[32:35]
	v_mfma_f32_16x16x32_bf16 v[20:23], v[194:197], v[178:181], v[20:23]
	v_mfma_f32_16x16x32_bf16 v[16:19], v[212:215], v[178:181], v[16:19]
	v_mfma_f32_16x16x32_bf16 v[4:7], v[194:197], v[186:189], v[4:7]
	v_mfma_f32_16x16x32_bf16 v[0:3], v[212:215], v[186:189], v[0:3]
	v_mfma_f32_16x16x32_bf16 v[52:55], v[208:211], v[166:169], v[52:55]
	v_mfma_f32_16x16x32_bf16 v[48:51], v[216:219], v[166:169], v[48:51]
	v_mfma_f32_16x16x32_bf16 v[36:39], v[208:211], v[174:177], v[36:39]
	v_mfma_f32_16x16x32_bf16 v[32:35], v[216:219], v[174:177], v[32:35]
	v_mfma_f32_16x16x32_bf16 v[20:23], v[208:211], v[182:185], v[20:23]
	v_mfma_f32_16x16x32_bf16 v[16:19], v[216:219], v[182:185], v[16:19]
	v_mfma_f32_16x16x32_bf16 v[4:7], v[208:211], v[190:193], v[4:7]
	v_mfma_f32_16x16x32_bf16 v[0:3], v[216:219], v[190:193], v[0:3]
	s_add_i32 s57, 0, 0x18000
	v_add_u32_e32 v158, s57, v201
	s_barrier
.Lg973_mid:
	s_add_u32 s20, s26, 0xb0000
	s_addc_u32 s21, s27, 0
	s_mov_b32 m0, s39
	s_nop 0
	global_load_lds_dwordx4 v128, s[20:21]
	s_mov_b32 m0, s40
	s_nop 0
	global_load_lds_dwordx4 v132, s[20:21]
	ds_read_b128 v[146:149], v158
	ds_read_b128 v[150:153], v158 offset:1024
	ds_read_b128 v[154:157], v158 offset:2048
	ds_read_b128 v[158:161], v158 offset:3072
	ds_read_b128 v[162:165], v204 offset:32768
	ds_read_b128 v[166:169], v204 offset:33792
	ds_read_b128 v[170:173], v204 offset:34816
	ds_read_b128 v[174:177], v204 offset:35840
	ds_read_b128 v[178:181], v204 offset:36864
	ds_read_b128 v[182:185], v204 offset:37888
	ds_read_b128 v[186:189], v204 offset:38912
	ds_read_b128 v[190:193], v204 offset:39936
	s_waitcnt lgkmcnt(8)
	s_barrier
	s_waitcnt lgkmcnt(0)
	s_waitcnt lgkmcnt(0)
	v_mfma_f32_16x16x32_bf16 v[124:127], v[146:149], v[162:165], v[124:127]
	v_mfma_f32_16x16x32_bf16 v[120:123], v[154:157], v[162:165], v[120:123]
	v_mfma_f32_16x16x32_bf16 v[108:111], v[146:149], v[170:173], v[108:111]
	v_mfma_f32_16x16x32_bf16 v[104:107], v[154:157], v[170:173], v[104:107]
	v_mfma_f32_16x16x32_bf16 v[92:95], v[146:149], v[178:181], v[92:95]
	v_mfma_f32_16x16x32_bf16 v[88:91], v[154:157], v[178:181], v[88:91]
	v_mfma_f32_16x16x32_bf16 v[76:79], v[146:149], v[186:189], v[76:79]
	v_mfma_f32_16x16x32_bf16 v[72:75], v[154:157], v[186:189], v[72:75]
	v_mfma_f32_16x16x32_bf16 v[124:127], v[150:153], v[166:169], v[124:127]
	v_mfma_f32_16x16x32_bf16 v[120:123], v[158:161], v[166:169], v[120:123]
	v_mfma_f32_16x16x32_bf16 v[108:111], v[150:153], v[174:177], v[108:111]
	v_mfma_f32_16x16x32_bf16 v[104:107], v[158:161], v[174:177], v[104:107]
	v_mfma_f32_16x16x32_bf16 v[92:95], v[150:153], v[182:185], v[92:95]
	v_mfma_f32_16x16x32_bf16 v[88:91], v[158:161], v[182:185], v[88:91]
	v_mfma_f32_16x16x32_bf16 v[76:79], v[150:153], v[190:193], v[76:79]
	v_mfma_f32_16x16x32_bf16 v[72:75], v[158:161], v[190:193], v[72:75]
	s_barrier
	s_add_i32 s26, 0, 0x1c000
	s_add_i32 s20, s57, s36
	v_add_u32_e32 v216, s26, v201
	s_mov_b32 m0, s20
	s_nop 0
	global_load_lds_dwordx4 v130, s[80:81]
	s_add_i32 m0, s20, 0x2000
	s_nop 0
	global_load_lds_dwordx4 v134, s[80:81]
	ds_read_b128 v[194:197], v216
	ds_read_b128 v[208:211], v216 offset:1024
	ds_read_b128 v[212:215], v216 offset:2048
	ds_read_b128 v[216:219], v216 offset:3072
	s_waitcnt vmcnt(10)
	s_barrier
	s_waitcnt lgkmcnt(0)
	s_waitcnt lgkmcnt(0)
	v_mfma_f32_16x16x32_bf16 v[116:119], v[194:197], v[162:165], v[116:119]
	v_mfma_f32_16x16x32_bf16 v[112:115], v[212:215], v[162:165], v[112:115]
	v_mfma_f32_16x16x32_bf16 v[100:103], v[194:197], v[170:173], v[100:103]
	v_mfma_f32_16x16x32_bf16 v[96:99], v[212:215], v[170:173], v[96:99]
	v_mfma_f32_16x16x32_bf16 v[84:87], v[194:197], v[178:181], v[84:87]
	v_mfma_f32_16x16x32_bf16 v[80:83], v[212:215], v[178:181], v[80:83]
	v_mfma_f32_16x16x32_bf16 v[68:71], v[194:197], v[186:189], v[68:71]
	v_mfma_f32_16x16x32_bf16 v[64:67], v[212:215], v[186:189], v[64:67]
	v_mfma_f32_16x16x32_bf16 v[116:119], v[208:211], v[166:169], v[116:119]
	v_mfma_f32_16x16x32_bf16 v[112:115], v[216:219], v[166:169], v[112:115]
	v_mfma_f32_16x16x32_bf16 v[100:103], v[208:211], v[174:177], v[100:103]
	v_mfma_f32_16x16x32_bf16 v[96:99], v[216:219], v[174:177], v[96:99]
	v_mfma_f32_16x16x32_bf16 v[84:87], v[208:211], v[182:185], v[84:87]
	v_mfma_f32_16x16x32_bf16 v[80:83], v[216:219], v[182:185], v[80:83]
	v_mfma_f32_16x16x32_bf16 v[68:71], v[208:211], v[190:193], v[68:71]
	v_mfma_f32_16x16x32_bf16 v[64:67], v[216:219], v[190:193], v[64:67]
	s_mov_b32 m0, s42
	s_barrier
	global_load_lds_dwordx4 v128, s[82:83]
	s_mov_b32 m0, s43
	s_nop 0
	global_load_lds_dwordx4 v132, s[82:83]
	ds_read_b128 v[162:165], v204 offset:49152
	ds_read_b128 v[166:169], v204 offset:50176
	ds_read_b128 v[170:173], v204 offset:51200
	ds_read_b128 v[174:177], v204 offset:52224
	ds_read_b128 v[178:181], v204 offset:53248
	ds_read_b128 v[182:185], v204 offset:54272
	ds_read_b128 v[186:189], v204 offset:55296
	ds_read_b128 v[190:193], v204 offset:56320
	s_barrier
	s_waitcnt lgkmcnt(0)
	s_waitcnt lgkmcnt(0)
	v_mfma_f32_16x16x32_bf16 v[60:63], v[146:149], v[162:165], v[60:63]
	v_mfma_f32_16x16x32_bf16 v[56:59], v[154:157], v[162:165], v[56:59]
	v_mfma_f32_16x16x32_bf16 v[44:47], v[146:149], v[170:173], v[44:47]
	v_mfma_f32_16x16x32_bf16 v[40:43], v[154:157], v[170:173], v[40:43]
	v_mfma_f32_16x16x32_bf16 v[28:31], v[146:149], v[178:181], v[28:31]
	v_mfma_f32_16x16x32_bf16 v[24:27], v[154:157], v[178:181], v[24:27]
	v_mfma_f32_16x16x32_bf16 v[12:15], v[146:149], v[186:189], v[12:15]
	v_mfma_f32_16x16x32_bf16 v[8:11], v[154:157], v[186:189], v[8:11]
	v_mfma_f32_16x16x32_bf16 v[60:63], v[150:153], v[166:169], v[60:63]
	v_mfma_f32_16x16x32_bf16 v[56:59], v[158:161], v[166:169], v[56:59]
	v_mfma_f32_16x16x32_bf16 v[44:47], v[150:153], v[174:177], v[44:47]
	v_mfma_f32_16x16x32_bf16 v[40:43], v[158:161], v[174:177], v[40:43]
	v_mfma_f32_16x16x32_bf16 v[28:31], v[150:153], v[182:185], v[28:31]
	v_mfma_f32_16x16x32_bf16 v[24:27], v[158:161], v[182:185], v[24:27]
	v_mfma_f32_16x16x32_bf16 v[12:15], v[150:153], v[190:193], v[12:15]
	v_mfma_f32_16x16x32_bf16 v[8:11], v[158:161], v[190:193], v[8:11]
	s_barrier
	s_add_u32 s20, s24, 0xb0080
	s_addc_u32 s21, s25, 0
	s_add_i32 s24, s26, s36
	s_mov_b32 m0, s24
	s_nop 0
	global_load_lds_dwordx4 v130, s[20:21]
	s_add_i32 m0, s24, 0x2000
	s_nop 0
	global_load_lds_dwordx4 v134, s[20:21]
	s_waitcnt vmcnt(8)
	s_barrier
	v_mfma_f32_16x16x32_bf16 v[52:55], v[194:197], v[162:165], v[52:55]
	v_mfma_f32_16x16x32_bf16 v[48:51], v[212:215], v[162:165], v[48:51]
	v_mfma_f32_16x16x32_bf16 v[36:39], v[194:197], v[170:173], v[36:39]
	v_mfma_f32_16x16x32_bf16 v[32:35], v[212:215], v[170:173], v[32:35]
	v_mfma_f32_16x16x32_bf16 v[20:23], v[194:197], v[178:181], v[20:23]
	v_mfma_f32_16x16x32_bf16 v[16:19], v[212:215], v[178:181], v[16:19]
	v_mfma_f32_16x16x32_bf16 v[4:7], v[194:197], v[186:189], v[4:7]
	v_mfma_f32_16x16x32_bf16 v[0:3], v[212:215], v[186:189], v[0:3]
	v_mfma_f32_16x16x32_bf16 v[52:55], v[208:211], v[166:169], v[52:55]
	v_mfma_f32_16x16x32_bf16 v[48:51], v[216:219], v[166:169], v[48:51]
	v_mfma_f32_16x16x32_bf16 v[36:39], v[208:211], v[174:177], v[36:39]
	v_mfma_f32_16x16x32_bf16 v[32:35], v[216:219], v[174:177], v[32:35]
	v_mfma_f32_16x16x32_bf16 v[20:23], v[208:211], v[182:185], v[20:23]
	v_mfma_f32_16x16x32_bf16 v[16:19], v[216:219], v[182:185], v[16:19]
	v_mfma_f32_16x16x32_bf16 v[4:7], v[208:211], v[190:193], v[4:7]
	v_mfma_f32_16x16x32_bf16 v[0:3], v[216:219], v[190:193], v[0:3]
	s_add_i32 s56, s56, 2
	s_add_u32 s54, s54, 0x100
	s_addc_u32 s55, s55, 0
	s_cmp_gt_u32 s56, 41
	s_mov_b64 s[20:21], s[22:23]
	s_barrier
	s_cbranch_scc0 .LBB0_973
	s_setprio 0
	s_cmpk_gt_u32 s30, 0xff
	s_cbranch_scc1 .Lg973_nox
	s_barrier
	s_setprio 1
